# relaxed first-iteration waits (vmcnt(22) for units after the first) on all six GEMM K-loops, flag computed at the unit-loop header
# baseline (speedup 1.0000x reference)
;     __device__ __forceinline__ bool next(int i, Unit& v) const { if (i != 0) return false; v = u; return true; }
;     __host__ __device__ bool next(int i, Unit& u) const { const long L = (long)i * G + c; if (L >= lim) return false; unit_of((int)L, u); return true; }
;     ...
;         const bool has_next = S.next(ui + 1, nxt);
;         if constexpr (TP == 3) { if (ui > 0) tp_acc += __builtin_amdgcn_s_memrealtime() - tp3; }
;         const char* nA = has_next ? (const char*)g.A + (size_t)nxt.pm * tstep : cA; const char* nB = has_next ? (const char*)g.Bt + (size_t)nxt.pn * tstep : cB;
.LBB0_227:
	s_cmp_lg_u32 s18, 0
	s_cselect_b32 s101, 1, 0
	s_add_i32 s30, s18, 1
	s_mul_i32 s0, s30, s59
	s_mul_hi_u32 s1, s30, s47
	s_add_i32 s1, s1, s0
	s_mul_i32 s0, s30, s47
	s_add_u32 s40, s0, s43
	s_addc_u32 s41, s1, s93
	v_mov_b64_e32 v[2:3], 0x800
	v_cmp_lt_i64_e64 s[6:7], s[40:41], v[2:3]
	v_mov_b64_e32 v[2:3], 0x7ff
	v_cmp_gt_i64_e32 vcc, s[40:41], v[2:3]
	s_cbranch_vccnz .LBB0_233
	s_ashr_i32 s0, s40, 31
	s_lshr_b32 s0, s0, 29
	s_add_i32 s0, s40, s0
	s_and_b32 s1, s0, -8
	s_sub_i32 s1, s40, s1
	s_cmp_gt_i32 s1, -1
	s_mov_b64 s[40:41], -1
	s_cbranch_scc0 .LBB0_230
	s_lshl_b32 s19, s1, 8
	s_mov_b64 s[40:41], 0

; #define PG8_STAGE(bufoff, gbase, voff) do { _Pragma("unroll") for (int _i = 0; _i < 2; ++_i) \
;         __builtin_amdgcn_global_load_lds((const unsigned*)((const char*)(gbase) + (voff)[_i]), (PG8_LAS unsigned*)(lds + (bufoff) + ldsw + _i * 8192), 16, 0, 0); } while (0)
; #define PG8_LDA(dst, b, h) do { _Pragma("unroll") for (int m = 0; m < 4; ++m) _Pragma("unroll") for (int k = 0; k < 2; ++k) dst[m][k] = *(const PG8_LAS bf16x8*)(lds + PG8_SA(b, h) + aoff + m * 2048 + k * 1024); } while (0)
; #define PG8_LDB(dst, b, h) do { _Pragma("unroll") for (int n = 0; n < 2; ++n) _Pragma("unroll") for (int k = 0; k < 2; ++k) dst[n][k] = *(const PG8_LAS bf16x8*)(lds + PG8_SB(b, h) + boff + n * 2048 + k * 1024); } while (0)
; #define PG8_WAIT_L(n) asm volatile("s_waitcnt lgkmcnt(" #n ")" ::: "memory")
; #define PG8_WAIT_V_SEL(sel) asm volatile("s_cmp_eq_u32 %0, 0\n\ts_cbranch_scc1 .Lw8_%=\n\ts_waitcnt vmcnt(22)\n\ts_branch .Lwd_%=\n.Lw8_%=:\n\ts_waitcnt vmcnt(8)\n.Lwd_%=:" :: "s"(sel) : "memory", "scc")
; #define PG8_BAR __builtin_amdgcn_s_barrier()
; #define PG8_SCHED __builtin_amdgcn_sched_barrier(0)
;     ...
;         for (int t = 0; t < nt * KREP; t += 2) {
;             const bool last = (t == nt * KREP - 2);
;             const int t1w = KREP > 1 ? ((t + 1) & (nt - 1)) : t + 1, t2w = KREP > 1 ? ((t + 2) & (nt - 1)) : t + 2;
;             const char* a1 = cA + (size_t)t1w * kstep;
;             const char* a2 = last ? nA : cA + (size_t)t2w * kstep; const char* b2 = last ? nB : cB + (size_t)t2w * kstep;
;             const char* a3 = a2 + kstep; const char* b3 = b2 + kstep;
;             if (last && has_next) S.a_ready(nxt);
;             const int relax = __builtin_amdgcn_readfirstlane((MK_RELAXW && t == 0 && ui > 0) ? 1 : 0);
;             if constexpr (SP2) {
;             PG8_LDB(B0, 0, 0); PG8_LDB(B1, 0, 1); PG8_SCHED; PG8_LDA(At, 0, 0); PG8_STAGE(PG8_SA(1, 1), a1 + hstep, voffA);
;             PG8_WAIT_V_SEL(relax);
;             PG8_WAIT_L(0); PG8_BAR; PG8_MMA(0, 0, At, B0); PG8_MMA(0, 1, At, B1); PG8_BAR; PG8_SCHED;
;             PG8_LDA(At, 0, 1); PG8_STAGE(PG8_SB(0, 0), b2, voffB); PG8_STAGE(PG8_SB(0, 1), b2 + hstep, voffB); PG8_STAGE(PG8_SA(0, 0), a2, voffA);
;             PG8_WAIT_V_SEL(relax);
;             PG8_WAIT_L(0); PG8_BAR; PG8_MMA(1, 0, At, B0); PG8_MMA(1, 1, At, B1); PG8_BAR; PG8_SCHED;
.LBB0_234:
	s_add_u32 s0, s78, 0xfff80080
	s_addc_u32 s1, s79, -1
	s_add_i32 s40, 0, 0x10000
	s_cmp_eq_u32 s37, 28
	s_cselect_b32 s83, s19, s1
	s_cselect_b32 s82, s20, s0
	s_cselect_b32 s81, s24, s35
	s_cselect_b32 s80, s31, s33
	s_add_i32 s41, 0, 0x14000
	ds_read_b128 v[142:145], v168
	ds_read_b128 v[146:149], v168 offset:1024
	ds_read_b128 v[150:153], v168 offset:2048
	ds_read_b128 v[154:157], v168 offset:3072
	ds_read_b128 v[158:161], v168 offset:16384
	ds_read_b128 v[162:165], v168 offset:17408
	ds_read_b128 v[174:177], v168 offset:18432
	ds_read_b128 v[188:191], v168 offset:19456
	s_add_i32 m0, s75, 0xc000
	ds_read_b128 v[198:201], v196
	ds_read_b128 v[202:205], v196 offset:1024
	ds_read_b128 v[206:209], v196 offset:2048
	ds_read_b128 v[210:213], v196 offset:3072
	ds_read_b128 v[214:217], v196 offset:4096
	ds_read_b128 v[218:221], v196 offset:5120
	ds_read_b128 v[222:225], v196 offset:6144
	ds_read_b128 v[226:229], v196 offset:7168
	global_load_lds_dwordx4 v138, s[78:79]
	s_add_i32 m0, s75, 0xe000
	s_nop 0
	global_load_lds_dwordx4 v140, s[78:79]
	s_cmp_eq_u32 s101, 1
	s_cbranch_scc1 .Lrlx_gi_0
	s_waitcnt vmcnt(8)
.Lrlx_gi_0_b:
	s_waitcnt lgkmcnt(0)
	s_setprio 1
	s_barrier
	v_mfma_f32_16x16x32_bf16 v[126:129], v[142:145], v[198:201], v[126:129]
	v_mfma_f32_16x16x32_bf16 v[126:129], v[146:149], v[202:205], v[126:129]
	v_mfma_f32_16x16x32_bf16 v[122:125], v[142:145], v[206:209], v[122:125]
	v_mfma_f32_16x16x32_bf16 v[122:125], v[146:149], v[210:213], v[122:125]
	v_mfma_f32_16x16x32_bf16 v[118:121], v[142:145], v[214:217], v[118:121]
	v_mfma_f32_16x16x32_bf16 v[118:121], v[146:149], v[218:221], v[118:121]
	v_mfma_f32_16x16x32_bf16 v[114:117], v[142:145], v[222:225], v[114:117]
	v_mfma_f32_16x16x32_bf16 v[114:117], v[146:149], v[226:229], v[114:117]
	v_mfma_f32_16x16x32_bf16 v[98:101], v[150:153], v[222:225], v[98:101]
	v_mfma_f32_16x16x32_bf16 v[98:101], v[154:157], v[226:229], v[98:101]
	v_mfma_f32_16x16x32_bf16 v[102:105], v[150:153], v[214:217], v[102:105]
	v_mfma_f32_16x16x32_bf16 v[102:105], v[154:157], v[218:221], v[102:105]
	v_mfma_f32_16x16x32_bf16 v[106:109], v[150:153], v[206:209], v[106:109]
	v_mfma_f32_16x16x32_bf16 v[106:109], v[154:157], v[210:213], v[106:109]
	v_mfma_f32_16x16x32_bf16 v[110:113], v[150:153], v[198:201], v[110:113]
	v_mfma_f32_16x16x32_bf16 v[110:113], v[154:157], v[202:205], v[110:113]
	v_mfma_f32_16x16x32_bf16 v[82:85], v[158:161], v[198:201], v[82:85]
	v_mfma_f32_16x16x32_bf16 v[82:85], v[162:165], v[202:205], v[82:85]
	v_mfma_f32_16x16x32_bf16 v[70:73], v[158:161], v[206:209], v[70:73]
	v_mfma_f32_16x16x32_bf16 v[70:73], v[162:165], v[210:213], v[70:73]
	v_mfma_f32_16x16x32_bf16 v[66:69], v[158:161], v[214:217], v[66:69]
	v_mfma_f32_16x16x32_bf16 v[66:69], v[162:165], v[218:221], v[66:69]
	v_mfma_f32_16x16x32_bf16 v[58:61], v[158:161], v[222:225], v[58:61]
	v_mfma_f32_16x16x32_bf16 v[58:61], v[162:165], v[226:229], v[58:61]
	v_mfma_f32_16x16x32_bf16 v[18:21], v[174:177], v[222:225], v[18:21]
	v_mfma_f32_16x16x32_bf16 v[18:21], v[188:191], v[226:229], v[18:21]
	v_mfma_f32_16x16x32_bf16 v[22:25], v[174:177], v[214:217], v[22:25]
	v_mfma_f32_16x16x32_bf16 v[22:25], v[188:191], v[218:221], v[22:25]
	v_mfma_f32_16x16x32_bf16 v[26:29], v[174:177], v[206:209], v[26:29]
	v_mfma_f32_16x16x32_bf16 v[26:29], v[188:191], v[210:213], v[26:29]
	v_mfma_f32_16x16x32_bf16 v[30:33], v[174:177], v[198:201], v[30:33]
	v_mfma_f32_16x16x32_bf16 v[30:33], v[188:191], v[202:205], v[30:33]
	s_barrier
	s_setprio 0
	s_add_i32 s0, s40, s87
	s_mov_b32 m0, s0
	ds_read_b128 v[198:201], v196 offset:16384
	ds_read_b128 v[202:205], v196 offset:17408
	ds_read_b128 v[206:209], v196 offset:18432
	ds_read_b128 v[210:213], v196 offset:19456
	ds_read_b128 v[214:217], v196 offset:20480
	ds_read_b128 v[218:221], v196 offset:21504
	ds_read_b128 v[222:225], v196 offset:22528
	ds_read_b128 v[226:229], v196 offset:23552
	global_load_lds_dwordx4 v182, s[80:81]
	s_add_i32 m0, s0, 0x2000
	s_add_u32 s0, s80, 0x80000
	s_addc_u32 s1, s81, 0
	s_add_i32 s40, s41, s87
	global_load_lds_dwordx4 v134, s[80:81]
	s_mov_b32 m0, s40
	s_nop 0
	global_load_lds_dwordx4 v182, s[0:1]
	s_add_i32 m0, s40, 0x2000
	s_nop 0
	global_load_lds_dwordx4 v134, s[0:1]
	s_mov_b32 m0, s75
	s_nop 0
	global_load_lds_dwordx4 v130, s[82:83]
	s_mov_b32 m0, s88
	s_nop 0
	global_load_lds_dwordx4 v132, s[82:83]
	s_cmp_eq_u32 s101, 1
	s_cbranch_scc1 .Lrlx_gi_1
	s_waitcnt vmcnt(8)
; #define PG8_STAGE(bufoff, gbase, voff) do { _Pragma("unroll") for (int _i = 0; _i < 2; ++_i) \
;         __builtin_amdgcn_global_load_lds((const unsigned*)((const char*)(gbase) + (voff)[_i]), (PG8_LAS unsigned*)(lds + (bufoff) + ldsw + _i * 8192), 16, 0, 0); } while (0)
; #define PG8_LDA(dst, b, h) do { _Pragma("unroll") for (int m = 0; m < 4; ++m) _Pragma("unroll") for (int k = 0; k < 2; ++k) dst[m][k] = *(const PG8_LAS bf16x8*)(lds + PG8_SA(b, h) + aoff + m * 2048 + k * 1024); } while (0)
; #define PG8_LDB(dst, b, h) do { _Pragma("unroll") for (int n = 0; n < 2; ++n) _Pragma("unroll") for (int k = 0; k < 2; ++k) dst[n][k] = *(const PG8_LAS bf16x8*)(lds + PG8_SB(b, h) + boff + n * 2048 + k * 1024); } while (0)
; #define PG8_WAIT_V(n) asm volatile("s_waitcnt vmcnt(" #n ")" ::: "memory")
; #define PG8_WAIT_L(n) asm volatile("s_waitcnt lgkmcnt(" #n ")" ::: "memory")
; #define PG8_BAR __builtin_amdgcn_s_barrier()
; #define PG8_SCHED __builtin_amdgcn_sched_barrier(0)
;     ...
;             PG8_WAIT_L(0); PG8_BAR; PG8_MMA(1, 0, At, B0); PG8_MMA(1, 1, At, B1); PG8_BAR; PG8_SCHED;
;             PG8_LDB(B0, 1, 0); PG8_LDB(B1, 1, 1); PG8_SCHED; PG8_LDA(At, 1, 0); PG8_STAGE(PG8_SA(0, 1), a2 + hstep, voffA);
;             PG8_WAIT_V(8); PG8_WAIT_L(0); PG8_BAR; PG8_MMA(0, 0, At, B0); PG8_MMA(0, 1, At, B1); PG8_BAR; PG8_SCHED;
;             PG8_LDA(At, 1, 1); PG8_STAGE(PG8_SB(1, 0), b3, voffB); PG8_STAGE(PG8_SB(1, 1), b3 + hstep, voffB); PG8_STAGE(PG8_SA(1, 0), a3, voffA);
.Lrlx_gi_1_b:
	s_waitcnt lgkmcnt(0)
	s_setprio 1
	s_barrier
	v_mfma_f32_16x16x32_bf16 v[94:97], v[142:145], v[198:201], v[94:97]
	v_mfma_f32_16x16x32_bf16 v[94:97], v[146:149], v[202:205], v[94:97]
	v_mfma_f32_16x16x32_bf16 v[90:93], v[142:145], v[206:209], v[90:93]
	v_mfma_f32_16x16x32_bf16 v[90:93], v[146:149], v[210:213], v[90:93]
	v_mfma_f32_16x16x32_bf16 v[86:89], v[142:145], v[214:217], v[86:89]
	v_mfma_f32_16x16x32_bf16 v[86:89], v[146:149], v[218:221], v[86:89]
	v_mfma_f32_16x16x32_bf16 v[78:81], v[142:145], v[222:225], v[78:81]
	v_mfma_f32_16x16x32_bf16 v[78:81], v[146:149], v[226:229], v[78:81]
	v_mfma_f32_16x16x32_bf16 v[50:53], v[150:153], v[222:225], v[50:53]
	v_mfma_f32_16x16x32_bf16 v[50:53], v[154:157], v[226:229], v[50:53]
	v_mfma_f32_16x16x32_bf16 v[54:57], v[150:153], v[214:217], v[54:57]
	v_mfma_f32_16x16x32_bf16 v[54:57], v[154:157], v[218:221], v[54:57]
	v_mfma_f32_16x16x32_bf16 v[62:65], v[150:153], v[206:209], v[62:65]
	v_mfma_f32_16x16x32_bf16 v[62:65], v[154:157], v[210:213], v[62:65]
	v_mfma_f32_16x16x32_bf16 v[74:77], v[150:153], v[198:201], v[74:77]
	v_mfma_f32_16x16x32_bf16 v[74:77], v[154:157], v[202:205], v[74:77]
	v_mfma_f32_16x16x32_bf16 v[46:49], v[158:161], v[198:201], v[46:49]
	v_mfma_f32_16x16x32_bf16 v[46:49], v[162:165], v[202:205], v[46:49]
	v_mfma_f32_16x16x32_bf16 v[42:45], v[158:161], v[206:209], v[42:45]
	v_mfma_f32_16x16x32_bf16 v[42:45], v[162:165], v[210:213], v[42:45]
	v_mfma_f32_16x16x32_bf16 v[38:41], v[158:161], v[214:217], v[38:41]
	v_mfma_f32_16x16x32_bf16 v[38:41], v[162:165], v[218:221], v[38:41]
	v_mfma_f32_16x16x32_bf16 v[34:37], v[158:161], v[222:225], v[34:37]
	v_mfma_f32_16x16x32_bf16 v[34:37], v[162:165], v[226:229], v[34:37]
	v_mfma_f32_16x16x32_bf16 v[2:5], v[174:177], v[222:225], v[2:5]
	v_mfma_f32_16x16x32_bf16 v[2:5], v[188:191], v[226:229], v[2:5]
	v_mfma_f32_16x16x32_bf16 v[6:9], v[174:177], v[214:217], v[6:9]
	v_mfma_f32_16x16x32_bf16 v[6:9], v[188:191], v[218:221], v[6:9]
	v_mfma_f32_16x16x32_bf16 v[10:13], v[174:177], v[206:209], v[10:13]
	v_mfma_f32_16x16x32_bf16 v[10:13], v[188:191], v[210:213], v[10:13]
	v_mfma_f32_16x16x32_bf16 v[14:17], v[174:177], v[198:201], v[14:17]
	v_mfma_f32_16x16x32_bf16 v[14:17], v[188:191], v[202:205], v[14:17]
	s_barrier
	s_setprio 0
	s_add_i32 s40, 0, 0x18000
	s_add_i32 s41, 0, 0x1c000
	ds_read_b128 v[142:145], v168 offset:32768
	ds_read_b128 v[146:149], v168 offset:33792
	ds_read_b128 v[150:153], v168 offset:34816
	ds_read_b128 v[154:157], v168 offset:35840
	ds_read_b128 v[158:161], v168 offset:49152
	ds_read_b128 v[162:165], v168 offset:50176
	ds_read_b128 v[174:177], v168 offset:51200
	ds_read_b128 v[188:191], v168 offset:52224
	s_add_u32 s0, s82, 0x80000
	s_addc_u32 s1, s83, 0
	s_mov_b32 m0, s89
	ds_read_b128 v[198:201], v196 offset:32768
	ds_read_b128 v[202:205], v196 offset:33792
	ds_read_b128 v[206:209], v196 offset:34816
	ds_read_b128 v[210:213], v196 offset:35840
	ds_read_b128 v[214:217], v196 offset:36864
	ds_read_b128 v[218:221], v196 offset:37888
	ds_read_b128 v[222:225], v196 offset:38912
	ds_read_b128 v[226:229], v196 offset:39936
	global_load_lds_dwordx4 v130, s[0:1]
	s_mov_b32 m0, s90
	s_nop 0
	global_load_lds_dwordx4 v132, s[0:1]
	s_waitcnt vmcnt(8)
	s_waitcnt lgkmcnt(0)
	s_setprio 1
	s_barrier
	v_mfma_f32_16x16x32_bf16 v[126:129], v[142:145], v[198:201], v[126:129]
	v_mfma_f32_16x16x32_bf16 v[126:129], v[146:149], v[202:205], v[126:129]
	v_mfma_f32_16x16x32_bf16 v[122:125], v[142:145], v[206:209], v[122:125]
	v_mfma_f32_16x16x32_bf16 v[122:125], v[146:149], v[210:213], v[122:125]
	v_mfma_f32_16x16x32_bf16 v[118:121], v[142:145], v[214:217], v[118:121]
	v_mfma_f32_16x16x32_bf16 v[118:121], v[146:149], v[218:221], v[118:121]
	v_mfma_f32_16x16x32_bf16 v[114:117], v[142:145], v[222:225], v[114:117]
	v_mfma_f32_16x16x32_bf16 v[114:117], v[146:149], v[226:229], v[114:117]
	v_mfma_f32_16x16x32_bf16 v[98:101], v[150:153], v[222:225], v[98:101]
	v_mfma_f32_16x16x32_bf16 v[98:101], v[154:157], v[226:229], v[98:101]
	v_mfma_f32_16x16x32_bf16 v[102:105], v[150:153], v[214:217], v[102:105]
	v_mfma_f32_16x16x32_bf16 v[102:105], v[154:157], v[218:221], v[102:105]
	v_mfma_f32_16x16x32_bf16 v[106:109], v[150:153], v[206:209], v[106:109]
	v_mfma_f32_16x16x32_bf16 v[106:109], v[154:157], v[210:213], v[106:109]
	v_mfma_f32_16x16x32_bf16 v[110:113], v[150:153], v[198:201], v[110:113]
	v_mfma_f32_16x16x32_bf16 v[110:113], v[154:157], v[202:205], v[110:113]
	v_mfma_f32_16x16x32_bf16 v[82:85], v[158:161], v[198:201], v[82:85]
	v_mfma_f32_16x16x32_bf16 v[82:85], v[162:165], v[202:205], v[82:85]
	v_mfma_f32_16x16x32_bf16 v[70:73], v[158:161], v[206:209], v[70:73]
	v_mfma_f32_16x16x32_bf16 v[70:73], v[162:165], v[210:213], v[70:73]
	v_mfma_f32_16x16x32_bf16 v[66:69], v[158:161], v[214:217], v[66:69]
	v_mfma_f32_16x16x32_bf16 v[66:69], v[162:165], v[218:221], v[66:69]
	v_mfma_f32_16x16x32_bf16 v[58:61], v[158:161], v[222:225], v[58:61]
	v_mfma_f32_16x16x32_bf16 v[58:61], v[162:165], v[226:229], v[58:61]
	v_mfma_f32_16x16x32_bf16 v[18:21], v[174:177], v[222:225], v[18:21]
	v_mfma_f32_16x16x32_bf16 v[18:21], v[188:191], v[226:229], v[18:21]
	v_mfma_f32_16x16x32_bf16 v[22:25], v[174:177], v[214:217], v[22:25]
	v_mfma_f32_16x16x32_bf16 v[22:25], v[188:191], v[218:221], v[22:25]
	v_mfma_f32_16x16x32_bf16 v[26:29], v[174:177], v[206:209], v[26:29]
	v_mfma_f32_16x16x32_bf16 v[26:29], v[188:191], v[210:213], v[26:29]
	v_mfma_f32_16x16x32_bf16 v[30:33], v[174:177], v[198:201], v[30:33]
	v_mfma_f32_16x16x32_bf16 v[30:33], v[188:191], v[202:205], v[30:33]
	s_barrier
; #define PG8_STAGE(bufoff, gbase, voff) do { _Pragma("unroll") for (int _i = 0; _i < 2; ++_i) \
;         __builtin_amdgcn_global_load_lds((const unsigned*)((const char*)(gbase) + (voff)[_i]), (PG8_LAS unsigned*)(lds + (bufoff) + ldsw + _i * 8192), 16, 0, 0); } while (0)
; #define PG8_LDA(dst, b, h) do { _Pragma("unroll") for (int m = 0; m < 4; ++m) _Pragma("unroll") for (int k = 0; k < 2; ++k) dst[m][k] = *(const PG8_LAS bf16x8*)(lds + PG8_SA(b, h) + aoff + m * 2048 + k * 1024); } while (0)
; #define PG8_WAIT_V(n) asm volatile("s_waitcnt vmcnt(" #n ")" ::: "memory")
; #define PG8_WAIT_L(n) asm volatile("s_waitcnt lgkmcnt(" #n ")" ::: "memory")
; #define PG8_BAR __builtin_amdgcn_s_barrier()
; #define PG8_SCHED __builtin_amdgcn_sched_barrier(0)
;     ...
;             PG8_LDA(At, 1, 1); PG8_STAGE(PG8_SB(1, 0), b3, voffB); PG8_STAGE(PG8_SB(1, 1), b3 + hstep, voffB); PG8_STAGE(PG8_SA(1, 0), a3, voffA);
;             PG8_WAIT_V(8); PG8_WAIT_L(0); PG8_BAR; PG8_MMA(1, 0, At, B0); PG8_MMA(1, 1, At, B1); PG8_BAR; PG8_SCHED;
	s_setprio 0
	s_add_i32 s0, s40, s87
	s_mov_b32 m0, s0
	ds_read_b128 v[198:201], v196 offset:49152
	ds_read_b128 v[202:205], v196 offset:50176
	ds_read_b128 v[206:209], v196 offset:51200
	ds_read_b128 v[210:213], v196 offset:52224
	ds_read_b128 v[214:217], v196 offset:53248
	ds_read_b128 v[218:221], v196 offset:54272
	ds_read_b128 v[222:225], v196 offset:55296
	ds_read_b128 v[226:229], v196 offset:56320
	s_add_u32 s100, s80, 0x80
	s_addc_u32 s101, s81, 0
	global_load_lds_dwordx4 v182, s[100:101]
	s_add_i32 m0, s0, 0x2000
	s_add_u32 s0, s80, 0x80080
	s_addc_u32 s1, s81, 0
	s_add_i32 s40, s41, s87
	global_load_lds_dwordx4 v134, s[100:101]
	s_mov_b32 m0, s40
	s_nop 0
	global_load_lds_dwordx4 v182, s[0:1]
	s_add_i32 m0, s40, 0x2000
	s_nop 0
	global_load_lds_dwordx4 v134, s[0:1]
	s_mov_b32 m0, s94
	s_nop 0
	s_add_u32 s100, s82, 0x80
	s_addc_u32 s101, s83, 0
	global_load_lds_dwordx4 v130, s[100:101]
	s_mov_b32 m0, s95
	s_nop 0
	global_load_lds_dwordx4 v132, s[100:101]
	s_waitcnt vmcnt(8)
	s_waitcnt lgkmcnt(0)
	s_setprio 1
	s_barrier
	v_mfma_f32_16x16x32_bf16 v[94:97], v[142:145], v[198:201], v[94:97]
	v_mfma_f32_16x16x32_bf16 v[94:97], v[146:149], v[202:205], v[94:97]
	v_mfma_f32_16x16x32_bf16 v[90:93], v[142:145], v[206:209], v[90:93]
	v_mfma_f32_16x16x32_bf16 v[90:93], v[146:149], v[210:213], v[90:93]
	v_mfma_f32_16x16x32_bf16 v[86:89], v[142:145], v[214:217], v[86:89]
	v_mfma_f32_16x16x32_bf16 v[86:89], v[146:149], v[218:221], v[86:89]
	v_mfma_f32_16x16x32_bf16 v[78:81], v[142:145], v[222:225], v[78:81]
	v_mfma_f32_16x16x32_bf16 v[78:81], v[146:149], v[226:229], v[78:81]
	v_mfma_f32_16x16x32_bf16 v[50:53], v[150:153], v[222:225], v[50:53]
	v_mfma_f32_16x16x32_bf16 v[50:53], v[154:157], v[226:229], v[50:53]
	v_mfma_f32_16x16x32_bf16 v[54:57], v[150:153], v[214:217], v[54:57]
	v_mfma_f32_16x16x32_bf16 v[54:57], v[154:157], v[218:221], v[54:57]
	v_mfma_f32_16x16x32_bf16 v[62:65], v[150:153], v[206:209], v[62:65]
	v_mfma_f32_16x16x32_bf16 v[62:65], v[154:157], v[210:213], v[62:65]
	v_mfma_f32_16x16x32_bf16 v[74:77], v[150:153], v[198:201], v[74:77]
	v_mfma_f32_16x16x32_bf16 v[74:77], v[154:157], v[202:205], v[74:77]
	v_mfma_f32_16x16x32_bf16 v[46:49], v[158:161], v[198:201], v[46:49]
	v_mfma_f32_16x16x32_bf16 v[46:49], v[162:165], v[202:205], v[46:49]
	v_mfma_f32_16x16x32_bf16 v[42:45], v[158:161], v[206:209], v[42:45]
	v_mfma_f32_16x16x32_bf16 v[42:45], v[162:165], v[210:213], v[42:45]
	v_mfma_f32_16x16x32_bf16 v[38:41], v[158:161], v[214:217], v[38:41]
	v_mfma_f32_16x16x32_bf16 v[38:41], v[162:165], v[218:221], v[38:41]
	v_mfma_f32_16x16x32_bf16 v[34:37], v[158:161], v[222:225], v[34:37]
	v_mfma_f32_16x16x32_bf16 v[34:37], v[162:165], v[226:229], v[34:37]
	v_mfma_f32_16x16x32_bf16 v[2:5], v[174:177], v[222:225], v[2:5]
	v_mfma_f32_16x16x32_bf16 v[2:5], v[188:191], v[226:229], v[2:5]
	v_mfma_f32_16x16x32_bf16 v[6:9], v[174:177], v[214:217], v[6:9]
	v_mfma_f32_16x16x32_bf16 v[6:9], v[188:191], v[218:221], v[6:9]
	v_mfma_f32_16x16x32_bf16 v[10:13], v[174:177], v[206:209], v[10:13]
	v_mfma_f32_16x16x32_bf16 v[10:13], v[188:191], v[210:213], v[10:13]
	v_mfma_f32_16x16x32_bf16 v[14:17], v[174:177], v[198:201], v[14:17]
	v_mfma_f32_16x16x32_bf16 v[14:17], v[188:191], v[202:205], v[14:17]
	s_barrier
	s_setprio 0
	s_add_i32 s37, s37, 2
	s_add_u32 s78, s78, 0x100
	s_addc_u32 s79, s79, 0
	s_add_u32 s33, s33, 0x100
	s_addc_u32 s35, s35, 0
	s_cmp_gt_u32 s37, 29
	s_mov_b32 s101, 0
	s_cbranch_scc0 .LBB0_234
	s_branch .Lrlx_gi_x

; #define PG8_BAR __builtin_amdgcn_s_barrier()
;     ...
;         }
;         unsigned long long tp0 = 0; if constexpr (TP == 1) tp0 = __builtin_amdgcn_s_memrealtime();
;         if constexpr (ALIGN_EPI) { if (wr == 0) PG8_BAR; }
.Lrlx_gi_x:
	s_and_b64 vcc, exec, s[64:65]
	s_cbranch_vccz .LBB0_237
	s_barrier

;     __device__ __forceinline__ bool next(int i, Unit& v) const { if (i != 0) return false; v = u; return true; }
;     __host__ __device__ bool next(int i, Unit& u) const { const long L = (long)i * G + c; if (L >= lim) return false; unit_of((int)L, u); return true; }
;     ...
;         const bool has_next = S.next(ui + 1, nxt);
;         if constexpr (TP == 3) { if (ui > 0) tp_acc += __builtin_amdgcn_s_memrealtime() - tp3; }
;         const char* nA = has_next ? (const char*)g.A + (size_t)nxt.pm * tstep : cA; const char* nB = has_next ? (const char*)g.Bt + (size_t)nxt.pn * tstep : cB;
.LBB0_534:
	s_cmp_lg_u32 s56, 0
	s_cselect_b32 s101, 1, 0
	s_add_i32 s51, s56, 1
	s_mul_i32 s0, s51, s26
	s_mul_hi_u32 s1, s51, s2
	s_add_i32 s1, s1, s0
	s_mul_i32 s0, s51, s2
	s_add_u32 s40, s0, s43
	s_addc_u32 s41, s1, s48
	v_mov_b64_e32 v[2:3], 0x3ff
	v_cmp_gt_i64_e32 vcc, s[40:41], v[2:3]
	v_cmp_lt_i64_e64 s[6:7], s[40:41], v[252:253]
	s_cbranch_vccnz .LBB0_540
	s_ashr_i32 s0, s40, 31
	s_lshr_b32 s0, s0, 29
	s_add_i32 s0, s40, s0
	s_and_b32 s1, s0, -8
	s_sub_i32 s1, s40, s1
	s_cmp_gt_i32 s1, -1
	s_mov_b64 s[40:41], -1
	s_cbranch_scc0 .LBB0_537
	s_lshl_b32 s57, s1, 7
	s_mov_b64 s[40:41], 0

; #define PG8_STAGE(bufoff, gbase, voff) do { _Pragma("unroll") for (int _i = 0; _i < 2; ++_i) \
;         __builtin_amdgcn_global_load_lds((const unsigned*)((const char*)(gbase) + (voff)[_i]), (PG8_LAS unsigned*)(lds + (bufoff) + ldsw + _i * 8192), 16, 0, 0); } while (0)
; #define PG8_LDA(dst, b, h) do { _Pragma("unroll") for (int m = 0; m < 4; ++m) _Pragma("unroll") for (int k = 0; k < 2; ++k) dst[m][k] = *(const PG8_LAS bf16x8*)(lds + PG8_SA(b, h) + aoff + m * 2048 + k * 1024); } while (0)
; #define PG8_LDB(dst, b, h) do { _Pragma("unroll") for (int n = 0; n < 2; ++n) _Pragma("unroll") for (int k = 0; k < 2; ++k) dst[n][k] = *(const PG8_LAS bf16x8*)(lds + PG8_SB(b, h) + boff + n * 2048 + k * 1024); } while (0)
; #define PG8_WAIT_L(n) asm volatile("s_waitcnt lgkmcnt(" #n ")" ::: "memory")
; #define PG8_WAIT_V_SEL(sel) asm volatile("s_cmp_eq_u32 %0, 0\n\ts_cbranch_scc1 .Lw8_%=\n\ts_waitcnt vmcnt(22)\n\ts_branch .Lwd_%=\n.Lw8_%=:\n\ts_waitcnt vmcnt(8)\n.Lwd_%=:" :: "s"(sel) : "memory", "scc")
; #define PG8_BAR __builtin_amdgcn_s_barrier()
; #define PG8_SCHED __builtin_amdgcn_sched_barrier(0)
;     ...
;         for (int t = 0; t < nt * KREP; t += 2) {
;             const bool last = (t == nt * KREP - 2);
;             const int t1w = KREP > 1 ? ((t + 1) & (nt - 1)) : t + 1, t2w = KREP > 1 ? ((t + 2) & (nt - 1)) : t + 2;
;             const char* a1 = cA + (size_t)t1w * kstep;
;             const char* a2 = last ? nA : cA + (size_t)t2w * kstep; const char* b2 = last ? nB : cB + (size_t)t2w * kstep;
;             const char* a3 = a2 + kstep; const char* b3 = b2 + kstep;
;             if (last && has_next) S.a_ready(nxt);
;             const int relax = __builtin_amdgcn_readfirstlane((MK_RELAXW && t == 0 && ui > 0) ? 1 : 0);
;             if constexpr (SP2) {
;             PG8_LDB(B0, 0, 0); PG8_LDB(B1, 0, 1); PG8_SCHED; PG8_LDA(At, 0, 0); PG8_STAGE(PG8_SA(1, 1), a1 + hstep, voffA);
;             PG8_WAIT_V_SEL(relax);
;             PG8_WAIT_L(0); PG8_BAR; PG8_MMA(0, 0, At, B0); PG8_MMA(0, 1, At, B1); PG8_BAR; PG8_SCHED;
;             PG8_LDA(At, 0, 1); PG8_STAGE(PG8_SB(0, 0), b2, voffB); PG8_STAGE(PG8_SB(0, 1), b2 + hstep, voffB); PG8_STAGE(PG8_SA(0, 0), a2, voffA);
;             PG8_WAIT_V_SEL(relax);
;             PG8_WAIT_L(0); PG8_BAR; PG8_MMA(1, 0, At, B0); PG8_MMA(1, 1, At, B1); PG8_BAR; PG8_SCHED;
.LBB0_541:
	s_add_u32 s0, s82, 0xfff80080
	s_addc_u32 s1, s83, -1
	s_add_i32 s79, 0, 0x10000
	s_cmp_eq_u32 s73, 28
	s_cselect_b32 s87, s40, s1
	s_cselect_b32 s86, s41, s0
	s_cselect_b32 s85, s57, s71
	s_cselect_b32 s84, s58, s59
	s_add_i32 s81, 0, 0x14000
	ds_read_b128 v[90:93], v210
	ds_read_b128 v[94:97], v210 offset:1024
	ds_read_b128 v[98:101], v210 offset:2048
	ds_read_b128 v[102:105], v210 offset:3072
	ds_read_b128 v[146:149], v210 offset:16384
	ds_read_b128 v[150:153], v210 offset:17408
	ds_read_b128 v[154:157], v210 offset:18432
	ds_read_b128 v[158:161], v210 offset:19456
	s_add_i32 m0, s44, 0xc000
	ds_read_b128 v[162:165], v230
	ds_read_b128 v[166:169], v230 offset:1024
	ds_read_b128 v[184:187], v230 offset:2048
	ds_read_b128 v[190:193], v230 offset:3072
	ds_read_b128 v[194:197], v230 offset:4096
	ds_read_b128 v[198:201], v230 offset:5120
	ds_read_b128 v[202:205], v230 offset:6144
	ds_read_b128 v[206:209], v230 offset:7168
	global_load_lds_dwordx4 v180, s[82:83]
	s_add_i32 m0, s44, 0xe000
	s_nop 0
	global_load_lds_dwordx4 v188, s[82:83]
	s_cmp_eq_u32 s101, 1
	s_cbranch_scc1 .Lrlx_go_0
	s_waitcnt vmcnt(8)
.Lrlx_go_0_b:
	s_waitcnt lgkmcnt(0)
	s_setprio 1
	s_barrier
	v_mfma_f32_16x16x32_bf16 v[142:145], v[90:93], v[162:165], v[142:145]
	v_mfma_f32_16x16x32_bf16 v[142:145], v[94:97], v[166:169], v[142:145]
	v_mfma_f32_16x16x32_bf16 v[126:129], v[90:93], v[184:187], v[126:129]
	v_mfma_f32_16x16x32_bf16 v[126:129], v[94:97], v[190:193], v[126:129]
	v_mfma_f32_16x16x32_bf16 v[110:113], v[90:93], v[194:197], v[110:113]
	v_mfma_f32_16x16x32_bf16 v[110:113], v[94:97], v[198:201], v[110:113]
	v_mfma_f32_16x16x32_bf16 v[78:81], v[90:93], v[202:205], v[78:81]
	v_mfma_f32_16x16x32_bf16 v[78:81], v[94:97], v[206:209], v[78:81]
	v_mfma_f32_16x16x32_bf16 v[74:77], v[98:101], v[202:205], v[74:77]
	v_mfma_f32_16x16x32_bf16 v[74:77], v[102:105], v[206:209], v[74:77]
	v_mfma_f32_16x16x32_bf16 v[106:109], v[98:101], v[194:197], v[106:109]
	v_mfma_f32_16x16x32_bf16 v[106:109], v[102:105], v[198:201], v[106:109]
	v_mfma_f32_16x16x32_bf16 v[122:125], v[98:101], v[184:187], v[122:125]
	v_mfma_f32_16x16x32_bf16 v[122:125], v[102:105], v[190:193], v[122:125]
	v_mfma_f32_16x16x32_bf16 v[138:141], v[98:101], v[162:165], v[138:141]
	v_mfma_f32_16x16x32_bf16 v[138:141], v[102:105], v[166:169], v[138:141]
	v_mfma_f32_16x16x32_bf16 v[134:137], v[146:149], v[162:165], v[134:137]
	v_mfma_f32_16x16x32_bf16 v[134:137], v[150:153], v[166:169], v[134:137]
	v_mfma_f32_16x16x32_bf16 v[118:121], v[146:149], v[184:187], v[118:121]
	v_mfma_f32_16x16x32_bf16 v[118:121], v[150:153], v[190:193], v[118:121]
	v_mfma_f32_16x16x32_bf16 v[86:89], v[146:149], v[194:197], v[86:89]
	v_mfma_f32_16x16x32_bf16 v[86:89], v[150:153], v[198:201], v[86:89]
	v_mfma_f32_16x16x32_bf16 v[70:73], v[146:149], v[202:205], v[70:73]
	v_mfma_f32_16x16x32_bf16 v[70:73], v[150:153], v[206:209], v[70:73]
	v_mfma_f32_16x16x32_bf16 v[66:69], v[154:157], v[202:205], v[66:69]
	v_mfma_f32_16x16x32_bf16 v[66:69], v[158:161], v[206:209], v[66:69]
	v_mfma_f32_16x16x32_bf16 v[82:85], v[154:157], v[194:197], v[82:85]
	v_mfma_f32_16x16x32_bf16 v[82:85], v[158:161], v[198:201], v[82:85]
	v_mfma_f32_16x16x32_bf16 v[114:117], v[154:157], v[184:187], v[114:117]
	v_mfma_f32_16x16x32_bf16 v[114:117], v[158:161], v[190:193], v[114:117]
	v_mfma_f32_16x16x32_bf16 v[130:133], v[154:157], v[162:165], v[130:133]
	v_mfma_f32_16x16x32_bf16 v[130:133], v[158:161], v[166:169], v[130:133]
	s_barrier
	s_setprio 0
	s_add_i32 s0, s79, s30
	s_mov_b32 m0, s0
	ds_read_b128 v[162:165], v230 offset:16384
	ds_read_b128 v[166:169], v230 offset:17408
	ds_read_b128 v[184:187], v230 offset:18432
	ds_read_b128 v[190:193], v230 offset:19456
	ds_read_b128 v[194:197], v230 offset:20480
	ds_read_b128 v[198:201], v230 offset:21504
	ds_read_b128 v[202:205], v230 offset:22528
	ds_read_b128 v[206:209], v230 offset:23552
	global_load_lds_dwordx4 v182, s[84:85]
	s_add_i32 m0, s0, 0x2000
	s_add_u32 s0, s84, 0x80000
	s_addc_u32 s1, s85, 0
	s_add_i32 s79, s81, s30
	global_load_lds_dwordx4 v178, s[84:85]
	s_mov_b32 m0, s79
	s_nop 0
	global_load_lds_dwordx4 v182, s[0:1]
	s_add_i32 m0, s79, 0x2000
	s_nop 0
	global_load_lds_dwordx4 v178, s[0:1]
	s_mov_b32 m0, s44
	s_nop 0
	global_load_lds_dwordx4 v174, s[86:87]
	s_mov_b32 m0, s45
	s_nop 0
	global_load_lds_dwordx4 v176, s[86:87]
	s_cmp_eq_u32 s101, 1
	s_cbranch_scc1 .Lrlx_go_1
	s_waitcnt vmcnt(8)
; #define PG8_STAGE(bufoff, gbase, voff) do { _Pragma("unroll") for (int _i = 0; _i < 2; ++_i) \
;         __builtin_amdgcn_global_load_lds((const unsigned*)((const char*)(gbase) + (voff)[_i]), (PG8_LAS unsigned*)(lds + (bufoff) + ldsw + _i * 8192), 16, 0, 0); } while (0)
; #define PG8_LDA(dst, b, h) do { _Pragma("unroll") for (int m = 0; m < 4; ++m) _Pragma("unroll") for (int k = 0; k < 2; ++k) dst[m][k] = *(const PG8_LAS bf16x8*)(lds + PG8_SA(b, h) + aoff + m * 2048 + k * 1024); } while (0)
; #define PG8_LDB(dst, b, h) do { _Pragma("unroll") for (int n = 0; n < 2; ++n) _Pragma("unroll") for (int k = 0; k < 2; ++k) dst[n][k] = *(const PG8_LAS bf16x8*)(lds + PG8_SB(b, h) + boff + n * 2048 + k * 1024); } while (0)
; #define PG8_WAIT_V(n) asm volatile("s_waitcnt vmcnt(" #n ")" ::: "memory")
; #define PG8_WAIT_L(n) asm volatile("s_waitcnt lgkmcnt(" #n ")" ::: "memory")
; #define PG8_BAR __builtin_amdgcn_s_barrier()
; #define PG8_SCHED __builtin_amdgcn_sched_barrier(0)
;     ...
;             PG8_WAIT_L(0); PG8_BAR; PG8_MMA(1, 0, At, B0); PG8_MMA(1, 1, At, B1); PG8_BAR; PG8_SCHED;
;             PG8_LDB(B0, 1, 0); PG8_LDB(B1, 1, 1); PG8_SCHED; PG8_LDA(At, 1, 0); PG8_STAGE(PG8_SA(0, 1), a2 + hstep, voffA);
;             PG8_WAIT_V(8); PG8_WAIT_L(0); PG8_BAR; PG8_MMA(0, 0, At, B0); PG8_MMA(0, 1, At, B1); PG8_BAR; PG8_SCHED;
;             PG8_LDA(At, 1, 1); PG8_STAGE(PG8_SB(1, 0), b3, voffB); PG8_STAGE(PG8_SB(1, 1), b3 + hstep, voffB); PG8_STAGE(PG8_SA(1, 0), a3, voffA);
.Lrlx_go_1_b:
	s_waitcnt lgkmcnt(0)
	s_setprio 1
	s_barrier
	v_mfma_f32_16x16x32_bf16 v[62:65], v[90:93], v[162:165], v[62:65]
	v_mfma_f32_16x16x32_bf16 v[62:65], v[94:97], v[166:169], v[62:65]
	v_mfma_f32_16x16x32_bf16 v[46:49], v[90:93], v[184:187], v[46:49]
	v_mfma_f32_16x16x32_bf16 v[46:49], v[94:97], v[190:193], v[46:49]
	v_mfma_f32_16x16x32_bf16 v[30:33], v[90:93], v[194:197], v[30:33]
	v_mfma_f32_16x16x32_bf16 v[30:33], v[94:97], v[198:201], v[30:33]
	v_mfma_f32_16x16x32_bf16 v[14:17], v[90:93], v[202:205], v[14:17]
	v_mfma_f32_16x16x32_bf16 v[14:17], v[94:97], v[206:209], v[14:17]
	v_mfma_f32_16x16x32_bf16 v[10:13], v[98:101], v[202:205], v[10:13]
	v_mfma_f32_16x16x32_bf16 v[10:13], v[102:105], v[206:209], v[10:13]
	v_mfma_f32_16x16x32_bf16 v[26:29], v[98:101], v[194:197], v[26:29]
	v_mfma_f32_16x16x32_bf16 v[26:29], v[102:105], v[198:201], v[26:29]
	v_mfma_f32_16x16x32_bf16 v[42:45], v[98:101], v[184:187], v[42:45]
	v_mfma_f32_16x16x32_bf16 v[42:45], v[102:105], v[190:193], v[42:45]
	v_mfma_f32_16x16x32_bf16 v[58:61], v[98:101], v[162:165], v[58:61]
	v_mfma_f32_16x16x32_bf16 v[58:61], v[102:105], v[166:169], v[58:61]
	v_mfma_f32_16x16x32_bf16 v[54:57], v[146:149], v[162:165], v[54:57]
	v_mfma_f32_16x16x32_bf16 v[54:57], v[150:153], v[166:169], v[54:57]
	v_mfma_f32_16x16x32_bf16 v[38:41], v[146:149], v[184:187], v[38:41]
	v_mfma_f32_16x16x32_bf16 v[38:41], v[150:153], v[190:193], v[38:41]
	v_mfma_f32_16x16x32_bf16 v[22:25], v[146:149], v[194:197], v[22:25]
	v_mfma_f32_16x16x32_bf16 v[22:25], v[150:153], v[198:201], v[22:25]
	v_mfma_f32_16x16x32_bf16 v[6:9], v[146:149], v[202:205], v[6:9]
	v_mfma_f32_16x16x32_bf16 v[6:9], v[150:153], v[206:209], v[6:9]
	v_mfma_f32_16x16x32_bf16 v[2:5], v[154:157], v[202:205], v[2:5]
	v_mfma_f32_16x16x32_bf16 v[2:5], v[158:161], v[206:209], v[2:5]
	v_mfma_f32_16x16x32_bf16 v[18:21], v[154:157], v[194:197], v[18:21]
	v_mfma_f32_16x16x32_bf16 v[18:21], v[158:161], v[198:201], v[18:21]
	v_mfma_f32_16x16x32_bf16 v[34:37], v[154:157], v[184:187], v[34:37]
	v_mfma_f32_16x16x32_bf16 v[34:37], v[158:161], v[190:193], v[34:37]
	v_mfma_f32_16x16x32_bf16 v[50:53], v[154:157], v[162:165], v[50:53]
	v_mfma_f32_16x16x32_bf16 v[50:53], v[158:161], v[166:169], v[50:53]
	s_barrier
	s_setprio 0
	s_add_i32 s79, 0, 0x18000
	s_add_i32 s81, 0, 0x1c000
	ds_read_b128 v[90:93], v210 offset:32768
	ds_read_b128 v[94:97], v210 offset:33792
	ds_read_b128 v[98:101], v210 offset:34816
	ds_read_b128 v[102:105], v210 offset:35840
	ds_read_b128 v[146:149], v210 offset:49152
	ds_read_b128 v[150:153], v210 offset:50176
	ds_read_b128 v[154:157], v210 offset:51200
	ds_read_b128 v[158:161], v210 offset:52224
	s_add_u32 s0, s86, 0x80000
	s_addc_u32 s1, s87, 0
	s_mov_b32 m0, s46
	ds_read_b128 v[162:165], v230 offset:32768
	ds_read_b128 v[166:169], v230 offset:33792
	ds_read_b128 v[184:187], v230 offset:34816
	ds_read_b128 v[190:193], v230 offset:35840
	ds_read_b128 v[194:197], v230 offset:36864
	ds_read_b128 v[198:201], v230 offset:37888
	ds_read_b128 v[202:205], v230 offset:38912
	ds_read_b128 v[206:209], v230 offset:39936
	global_load_lds_dwordx4 v174, s[0:1]
	s_mov_b32 m0, s47
	s_nop 0
	global_load_lds_dwordx4 v176, s[0:1]
	s_waitcnt vmcnt(8)
	s_waitcnt lgkmcnt(0)
	s_setprio 1
	s_barrier
	v_mfma_f32_16x16x32_bf16 v[142:145], v[90:93], v[162:165], v[142:145]
	v_mfma_f32_16x16x32_bf16 v[142:145], v[94:97], v[166:169], v[142:145]
	v_mfma_f32_16x16x32_bf16 v[126:129], v[90:93], v[184:187], v[126:129]
	v_mfma_f32_16x16x32_bf16 v[126:129], v[94:97], v[190:193], v[126:129]
	v_mfma_f32_16x16x32_bf16 v[110:113], v[90:93], v[194:197], v[110:113]
	v_mfma_f32_16x16x32_bf16 v[110:113], v[94:97], v[198:201], v[110:113]
	v_mfma_f32_16x16x32_bf16 v[78:81], v[90:93], v[202:205], v[78:81]
	v_mfma_f32_16x16x32_bf16 v[78:81], v[94:97], v[206:209], v[78:81]
	v_mfma_f32_16x16x32_bf16 v[74:77], v[98:101], v[202:205], v[74:77]
	v_mfma_f32_16x16x32_bf16 v[74:77], v[102:105], v[206:209], v[74:77]
	v_mfma_f32_16x16x32_bf16 v[106:109], v[98:101], v[194:197], v[106:109]
	v_mfma_f32_16x16x32_bf16 v[106:109], v[102:105], v[198:201], v[106:109]
	v_mfma_f32_16x16x32_bf16 v[122:125], v[98:101], v[184:187], v[122:125]
	v_mfma_f32_16x16x32_bf16 v[122:125], v[102:105], v[190:193], v[122:125]
	v_mfma_f32_16x16x32_bf16 v[138:141], v[98:101], v[162:165], v[138:141]
	v_mfma_f32_16x16x32_bf16 v[138:141], v[102:105], v[166:169], v[138:141]
	v_mfma_f32_16x16x32_bf16 v[134:137], v[146:149], v[162:165], v[134:137]
	v_mfma_f32_16x16x32_bf16 v[134:137], v[150:153], v[166:169], v[134:137]
	v_mfma_f32_16x16x32_bf16 v[118:121], v[146:149], v[184:187], v[118:121]
	v_mfma_f32_16x16x32_bf16 v[118:121], v[150:153], v[190:193], v[118:121]
	v_mfma_f32_16x16x32_bf16 v[86:89], v[146:149], v[194:197], v[86:89]
	v_mfma_f32_16x16x32_bf16 v[86:89], v[150:153], v[198:201], v[86:89]
	v_mfma_f32_16x16x32_bf16 v[70:73], v[146:149], v[202:205], v[70:73]
	v_mfma_f32_16x16x32_bf16 v[70:73], v[150:153], v[206:209], v[70:73]
	v_mfma_f32_16x16x32_bf16 v[66:69], v[154:157], v[202:205], v[66:69]
	v_mfma_f32_16x16x32_bf16 v[66:69], v[158:161], v[206:209], v[66:69]
	v_mfma_f32_16x16x32_bf16 v[82:85], v[154:157], v[194:197], v[82:85]
	v_mfma_f32_16x16x32_bf16 v[82:85], v[158:161], v[198:201], v[82:85]
	v_mfma_f32_16x16x32_bf16 v[114:117], v[154:157], v[184:187], v[114:117]
	v_mfma_f32_16x16x32_bf16 v[114:117], v[158:161], v[190:193], v[114:117]
	v_mfma_f32_16x16x32_bf16 v[130:133], v[154:157], v[162:165], v[130:133]
	v_mfma_f32_16x16x32_bf16 v[130:133], v[158:161], v[166:169], v[130:133]
	s_barrier
; #define PG8_STAGE(bufoff, gbase, voff) do { _Pragma("unroll") for (int _i = 0; _i < 2; ++_i) \
;         __builtin_amdgcn_global_load_lds((const unsigned*)((const char*)(gbase) + (voff)[_i]), (PG8_LAS unsigned*)(lds + (bufoff) + ldsw + _i * 8192), 16, 0, 0); } while (0)
; #define PG8_LDA(dst, b, h) do { _Pragma("unroll") for (int m = 0; m < 4; ++m) _Pragma("unroll") for (int k = 0; k < 2; ++k) dst[m][k] = *(const PG8_LAS bf16x8*)(lds + PG8_SA(b, h) + aoff + m * 2048 + k * 1024); } while (0)
; #define PG8_WAIT_V(n) asm volatile("s_waitcnt vmcnt(" #n ")" ::: "memory")
; #define PG8_WAIT_L(n) asm volatile("s_waitcnt lgkmcnt(" #n ")" ::: "memory")
; #define PG8_BAR __builtin_amdgcn_s_barrier()
; #define PG8_SCHED __builtin_amdgcn_sched_barrier(0)
;     ...
;             PG8_LDA(At, 1, 1); PG8_STAGE(PG8_SB(1, 0), b3, voffB); PG8_STAGE(PG8_SB(1, 1), b3 + hstep, voffB); PG8_STAGE(PG8_SA(1, 0), a3, voffA);
;             PG8_WAIT_V(8); PG8_WAIT_L(0); PG8_BAR; PG8_MMA(1, 0, At, B0); PG8_MMA(1, 1, At, B1); PG8_BAR; PG8_SCHED;
	s_setprio 0
	s_add_i32 s0, s79, s30
	s_mov_b32 m0, s0
	ds_read_b128 v[162:165], v230 offset:49152
	ds_read_b128 v[166:169], v230 offset:50176
	ds_read_b128 v[184:187], v230 offset:51200
	ds_read_b128 v[190:193], v230 offset:52224
	ds_read_b128 v[194:197], v230 offset:53248
	ds_read_b128 v[198:201], v230 offset:54272
	ds_read_b128 v[202:205], v230 offset:55296
	ds_read_b128 v[206:209], v230 offset:56320
	s_add_u32 s100, s84, 0x80
	s_addc_u32 s101, s85, 0
	global_load_lds_dwordx4 v182, s[100:101]
	s_add_i32 m0, s0, 0x2000
	s_add_u32 s0, s84, 0x80080
	s_addc_u32 s1, s85, 0
	s_add_i32 s79, s81, s30
	global_load_lds_dwordx4 v178, s[100:101]
	s_mov_b32 m0, s79
	s_nop 0
	global_load_lds_dwordx4 v182, s[0:1]
	s_add_i32 m0, s79, 0x2000
	s_nop 0
	global_load_lds_dwordx4 v178, s[0:1]
	s_mov_b32 m0, s49
	s_nop 0
	s_add_u32 s100, s86, 0x80
	s_addc_u32 s101, s87, 0
	global_load_lds_dwordx4 v174, s[100:101]
	s_mov_b32 m0, s50
	s_nop 0
	global_load_lds_dwordx4 v176, s[100:101]
	s_waitcnt vmcnt(8)
	s_waitcnt lgkmcnt(0)
	s_setprio 1
	s_barrier
	v_mfma_f32_16x16x32_bf16 v[62:65], v[90:93], v[162:165], v[62:65]
	v_mfma_f32_16x16x32_bf16 v[62:65], v[94:97], v[166:169], v[62:65]
	v_mfma_f32_16x16x32_bf16 v[46:49], v[90:93], v[184:187], v[46:49]
	v_mfma_f32_16x16x32_bf16 v[46:49], v[94:97], v[190:193], v[46:49]
	v_mfma_f32_16x16x32_bf16 v[30:33], v[90:93], v[194:197], v[30:33]
	v_mfma_f32_16x16x32_bf16 v[30:33], v[94:97], v[198:201], v[30:33]
	v_mfma_f32_16x16x32_bf16 v[14:17], v[90:93], v[202:205], v[14:17]
	v_mfma_f32_16x16x32_bf16 v[14:17], v[94:97], v[206:209], v[14:17]
	v_mfma_f32_16x16x32_bf16 v[10:13], v[98:101], v[202:205], v[10:13]
	v_mfma_f32_16x16x32_bf16 v[10:13], v[102:105], v[206:209], v[10:13]
	v_mfma_f32_16x16x32_bf16 v[26:29], v[98:101], v[194:197], v[26:29]
	v_mfma_f32_16x16x32_bf16 v[26:29], v[102:105], v[198:201], v[26:29]
	v_mfma_f32_16x16x32_bf16 v[42:45], v[98:101], v[184:187], v[42:45]
	v_mfma_f32_16x16x32_bf16 v[42:45], v[102:105], v[190:193], v[42:45]
	v_mfma_f32_16x16x32_bf16 v[58:61], v[98:101], v[162:165], v[58:61]
	v_mfma_f32_16x16x32_bf16 v[58:61], v[102:105], v[166:169], v[58:61]
	v_mfma_f32_16x16x32_bf16 v[54:57], v[146:149], v[162:165], v[54:57]
	v_mfma_f32_16x16x32_bf16 v[54:57], v[150:153], v[166:169], v[54:57]
	v_mfma_f32_16x16x32_bf16 v[38:41], v[146:149], v[184:187], v[38:41]
	v_mfma_f32_16x16x32_bf16 v[38:41], v[150:153], v[190:193], v[38:41]
	v_mfma_f32_16x16x32_bf16 v[22:25], v[146:149], v[194:197], v[22:25]
	v_mfma_f32_16x16x32_bf16 v[22:25], v[150:153], v[198:201], v[22:25]
	v_mfma_f32_16x16x32_bf16 v[6:9], v[146:149], v[202:205], v[6:9]
	v_mfma_f32_16x16x32_bf16 v[6:9], v[150:153], v[206:209], v[6:9]
	v_mfma_f32_16x16x32_bf16 v[2:5], v[154:157], v[202:205], v[2:5]
	v_mfma_f32_16x16x32_bf16 v[2:5], v[158:161], v[206:209], v[2:5]
	v_mfma_f32_16x16x32_bf16 v[18:21], v[154:157], v[194:197], v[18:21]
	v_mfma_f32_16x16x32_bf16 v[18:21], v[158:161], v[198:201], v[18:21]
	v_mfma_f32_16x16x32_bf16 v[34:37], v[154:157], v[184:187], v[34:37]
	v_mfma_f32_16x16x32_bf16 v[34:37], v[158:161], v[190:193], v[34:37]
	v_mfma_f32_16x16x32_bf16 v[50:53], v[154:157], v[162:165], v[50:53]
	v_mfma_f32_16x16x32_bf16 v[50:53], v[158:161], v[166:169], v[50:53]
	s_barrier
	s_setprio 0
	s_add_i32 s73, s73, 2
	s_add_u32 s82, s82, 0x100
	s_addc_u32 s83, s83, 0
	s_add_u32 s59, s59, 0x100
	s_addc_u32 s71, s71, 0
	s_cmp_gt_u32 s73, 29
	s_mov_b32 s101, 0
	s_cbranch_scc0 .LBB0_541
	s_branch .Lrlx_go_x

; #define PG8_BAR __builtin_amdgcn_s_barrier()
;     ...
;         }
;         unsigned long long tp0 = 0; if constexpr (TP == 1) tp0 = __builtin_amdgcn_s_memrealtime();
;         if constexpr (ALIGN_EPI) { if (wr == 0) PG8_BAR; }
.Lrlx_go_x:
	s_and_b64 vcc, exec, s[68:69]
	s_cbranch_vccz .LBB0_544
	s_barrier

;     __device__ __forceinline__ bool next(int i, Unit& v) const { if (i != 0) return false; v = u; return true; }
;     __host__ __device__ bool next(int i, Unit& u) const { const long L = (long)i * G + c; if (L >= lim) return false; unit_of((int)L, u); return true; }
;     ...
;         const bool has_next = S.next(ui + 1, nxt);
;         if constexpr (TP == 3) { if (ui > 0) tp_acc += __builtin_amdgcn_s_memrealtime() - tp3; }
;         const char* nA = has_next ? (const char*)g.A + (size_t)nxt.pm * tstep : cA; const char* nB = has_next ? (const char*)g.Bt + (size_t)nxt.pn * tstep : cB;
.LBB0_593:
	s_cmp_lg_u32 s26, 0
	s_cselect_b32 s101, 1, 0
	s_add_i32 s58, s26, 1
	s_mul_i32 s0, s58, s47
	s_mul_hi_u32 s1, s58, s18
	s_add_i32 s1, s1, s0
	s_mul_i32 s0, s58, s18
	s_add_u32 s40, s0, s96
	s_addc_u32 s41, s1, s19
	v_mov_b64_e32 v[2:3], 0xc00
	v_cmp_lt_i64_e64 s[2:3], s[40:41], v[2:3]
	v_mov_b64_e32 v[2:3], 0xbff
	v_cmp_gt_i64_e32 vcc, s[40:41], v[2:3]
	s_cbranch_vccnz .LBB0_595
	s_ashr_i32 s0, s40, 31
	s_lshr_b32 s0, s0, 29
	s_add_i32 s0, s40, s0
	s_ashr_i32 s1, s0, 3
	s_and_b32 s0, s0, -8
	s_sub_i32 s0, s40, s0
	s_cmp_lt_i32 s0, 0
	s_movk_i32 s40, 0x181
	s_cselect_b32 s40, s40, 0x180
	s_mul_i32 s0, s0, s40
	s_add_i32 s0, s0, s1
	s_mul_hi_i32 s1, s0, 0x2aaaaaab
	s_lshr_b32 s40, s1, 31
	s_ashr_i32 s1, s1, 4
	s_add_i32 s1, s1, s40
	s_lshl_b32 s40, s1, 2
	s_sub_i32 s41, 0x80, s40
	s_min_i32 s41, s41, 4
	s_abs_i32 s64, s41
	v_cvt_f32_u32_e32 v2, s64
	s_sub_i32 s66, 0, s64
	s_mulk_i32 s1, 0x60
	s_sub_i32 s0, s0, s1
	v_rcp_iflag_f32_e32 v2, v2
	s_abs_i32 s1, s0
	s_xor_b32 s65, s0, s41
	s_ashr_i32 s65, s65, 31
	v_mul_f32_e32 v2, 0x4f7ffffe, v2
	v_cvt_u32_f32_e32 v2, v2
	s_nop 0
	v_readfirstlane_b32 s67, v2
	s_mul_i32 s66, s66, s67
	s_mul_hi_u32 s66, s67, s66
	s_add_i32 s67, s67, s66
	s_mul_hi_u32 s66, s1, s67
	s_mul_i32 s67, s66, s64
	s_sub_i32 s1, s1, s67
	s_add_i32 s68, s66, 1
	s_sub_i32 s67, s1, s64
	s_cmp_ge_u32 s1, s64
	s_cselect_b32 s66, s68, s66
	s_cselect_b32 s1, s67, s1
	s_add_i32 s67, s66, 1
	s_cmp_ge_u32 s1, s64
	s_cselect_b32 s1, s67, s66
	s_xor_b32 s1, s1, s65
	s_sub_i32 s64, s1, s65
	s_mul_i32 s1, s64, s41
	s_sub_i32 s0, s0, s1
	s_add_i32 s66, s40, s0

; #define PG8_STAGE(bufoff, gbase, voff) do { _Pragma("unroll") for (int _i = 0; _i < 2; ++_i) \
;         __builtin_amdgcn_global_load_lds((const unsigned*)((const char*)(gbase) + (voff)[_i]), (PG8_LAS unsigned*)(lds + (bufoff) + ldsw + _i * 8192), 16, 0, 0); } while (0)
; #define PG8_LDA(dst, b, h) do { _Pragma("unroll") for (int m = 0; m < 4; ++m) _Pragma("unroll") for (int k = 0; k < 2; ++k) dst[m][k] = *(const PG8_LAS bf16x8*)(lds + PG8_SA(b, h) + aoff + m * 2048 + k * 1024); } while (0)
; #define PG8_LDB(dst, b, h) do { _Pragma("unroll") for (int n = 0; n < 2; ++n) _Pragma("unroll") for (int k = 0; k < 2; ++k) dst[n][k] = *(const PG8_LAS bf16x8*)(lds + PG8_SB(b, h) + boff + n * 2048 + k * 1024); } while (0)
; #define PG8_WAIT_L(n) asm volatile("s_waitcnt lgkmcnt(" #n ")" ::: "memory")
; #define PG8_WAIT_V_SEL(sel) asm volatile("s_cmp_eq_u32 %0, 0\n\ts_cbranch_scc1 .Lw8_%=\n\ts_waitcnt vmcnt(22)\n\ts_branch .Lwd_%=\n.Lw8_%=:\n\ts_waitcnt vmcnt(8)\n.Lwd_%=:" :: "s"(sel) : "memory", "scc")
; #define PG8_BAR __builtin_amdgcn_s_barrier()
; #define PG8_SCHED __builtin_amdgcn_sched_barrier(0)
;     ...
;         for (int t = 0; t < nt * KREP; t += 2) {
;             const bool last = (t == nt * KREP - 2);
;             const int t1w = KREP > 1 ? ((t + 1) & (nt - 1)) : t + 1, t2w = KREP > 1 ? ((t + 2) & (nt - 1)) : t + 2;
;             const char* a1 = cA + (size_t)t1w * kstep;
;             const char* a2 = last ? nA : cA + (size_t)t2w * kstep; const char* b2 = last ? nB : cB + (size_t)t2w * kstep;
;             const char* a3 = a2 + kstep; const char* b3 = b2 + kstep;
;             if (last && has_next) S.a_ready(nxt);
;             const int relax = __builtin_amdgcn_readfirstlane((MK_RELAXW && t == 0 && ui > 0) ? 1 : 0);
;             if constexpr (SP2) {
;             PG8_LDB(B0, 0, 0); PG8_LDB(B1, 0, 1); PG8_SCHED; PG8_LDA(At, 0, 0); PG8_STAGE(PG8_SA(1, 1), a1 + hstep, voffA);
;             PG8_WAIT_V_SEL(relax);
;             PG8_WAIT_L(0); PG8_BAR; PG8_MMA(0, 0, At, B0); PG8_MMA(0, 1, At, B1); PG8_BAR; PG8_SCHED;
;             PG8_LDA(At, 0, 1); PG8_STAGE(PG8_SB(0, 0), b2, voffB); PG8_STAGE(PG8_SB(0, 1), b2 + hstep, voffB); PG8_STAGE(PG8_SA(0, 0), a2, voffA);
;             PG8_WAIT_V_SEL(relax);
;             PG8_WAIT_L(0); PG8_BAR; PG8_MMA(1, 0, At, B0); PG8_MMA(1, 1, At, B1); PG8_BAR; PG8_SCHED;
.LBB0_596:
	s_add_u32 s0, s74, 0xfff80080
	s_addc_u32 s1, s75, -1
	s_add_i32 s83, 0, 0x10000
	s_cmp_eq_u32 s82, 28
	s_cselect_b32 s79, s40, s1
	s_cselect_b32 s78, s41, s0
	s_cselect_b32 s77, s65, s81
	s_cselect_b32 s76, s73, s80
	s_add_i32 s84, 0, 0x14000
	ds_read_b128 v[150:153], v180
	ds_read_b128 v[154:157], v180 offset:1024
	ds_read_b128 v[158:161], v180 offset:2048
	ds_read_b128 v[162:165], v180 offset:3072
	ds_read_b128 v[166:169], v180 offset:16384
	ds_read_b128 v[172:175], v180 offset:17408
	ds_read_b128 v[176:179], v180 offset:18432
	ds_read_b128 v[188:191], v180 offset:19456
	s_add_i32 m0, s35, 0xc000
	ds_read_b128 v[192:195], v148
	ds_read_b128 v[196:199], v148 offset:1024
	ds_read_b128 v[200:203], v148 offset:2048
	ds_read_b128 v[204:207], v148 offset:3072
	ds_read_b128 v[208:211], v148 offset:4096
	ds_read_b128 v[212:215], v148 offset:5120
	ds_read_b128 v[216:219], v148 offset:6144
	ds_read_b128 v[220:223], v148 offset:7168
	global_load_lds_dwordx4 v140, s[74:75]
	s_add_i32 m0, s35, 0xe000
	s_nop 0
	global_load_lds_dwordx4 v142, s[74:75]
	s_cmp_eq_u32 s101, 1
	s_cbranch_scc1 .Lrlx_qkv_0
	s_waitcnt vmcnt(8)
.Lrlx_qkv_0_b:
	s_waitcnt lgkmcnt(0)
	s_setprio 1
	s_barrier
	v_mfma_f32_16x16x32_bf16 v[126:129], v[150:153], v[192:195], v[126:129]
	v_mfma_f32_16x16x32_bf16 v[126:129], v[154:157], v[196:199], v[126:129]
	v_mfma_f32_16x16x32_bf16 v[122:125], v[150:153], v[200:203], v[122:125]
	v_mfma_f32_16x16x32_bf16 v[122:125], v[154:157], v[204:207], v[122:125]
	v_mfma_f32_16x16x32_bf16 v[118:121], v[150:153], v[208:211], v[118:121]
	v_mfma_f32_16x16x32_bf16 v[118:121], v[154:157], v[212:215], v[118:121]
	v_mfma_f32_16x16x32_bf16 v[114:117], v[150:153], v[216:219], v[114:117]
	v_mfma_f32_16x16x32_bf16 v[114:117], v[154:157], v[220:223], v[114:117]
	v_mfma_f32_16x16x32_bf16 v[98:101], v[158:161], v[216:219], v[98:101]
	v_mfma_f32_16x16x32_bf16 v[98:101], v[162:165], v[220:223], v[98:101]
	v_mfma_f32_16x16x32_bf16 v[102:105], v[158:161], v[208:211], v[102:105]
	v_mfma_f32_16x16x32_bf16 v[102:105], v[162:165], v[212:215], v[102:105]
	v_mfma_f32_16x16x32_bf16 v[106:109], v[158:161], v[200:203], v[106:109]
	v_mfma_f32_16x16x32_bf16 v[106:109], v[162:165], v[204:207], v[106:109]
	v_mfma_f32_16x16x32_bf16 v[110:113], v[158:161], v[192:195], v[110:113]
	v_mfma_f32_16x16x32_bf16 v[110:113], v[162:165], v[196:199], v[110:113]
	v_mfma_f32_16x16x32_bf16 v[70:73], v[166:169], v[192:195], v[70:73]
	v_mfma_f32_16x16x32_bf16 v[70:73], v[172:175], v[196:199], v[70:73]
	v_mfma_f32_16x16x32_bf16 v[66:69], v[166:169], v[200:203], v[66:69]
	v_mfma_f32_16x16x32_bf16 v[66:69], v[172:175], v[204:207], v[66:69]
	v_mfma_f32_16x16x32_bf16 v[58:61], v[166:169], v[208:211], v[58:61]
	v_mfma_f32_16x16x32_bf16 v[58:61], v[172:175], v[212:215], v[58:61]
	v_mfma_f32_16x16x32_bf16 v[46:49], v[166:169], v[216:219], v[46:49]
	v_mfma_f32_16x16x32_bf16 v[46:49], v[172:175], v[220:223], v[46:49]
	v_mfma_f32_16x16x32_bf16 v[34:37], v[176:179], v[216:219], v[34:37]
	v_mfma_f32_16x16x32_bf16 v[34:37], v[188:191], v[220:223], v[34:37]
	v_mfma_f32_16x16x32_bf16 v[38:41], v[176:179], v[208:211], v[38:41]
	v_mfma_f32_16x16x32_bf16 v[38:41], v[188:191], v[212:215], v[38:41]
	v_mfma_f32_16x16x32_bf16 v[42:45], v[176:179], v[200:203], v[42:45]
	v_mfma_f32_16x16x32_bf16 v[42:45], v[188:191], v[204:207], v[42:45]
	v_mfma_f32_16x16x32_bf16 v[50:53], v[176:179], v[192:195], v[50:53]
	v_mfma_f32_16x16x32_bf16 v[50:53], v[188:191], v[196:199], v[50:53]
	s_barrier
	s_setprio 0
	s_add_i32 s0, s83, s20
	s_mov_b32 m0, s0
	ds_read_b128 v[192:195], v148 offset:16384
	ds_read_b128 v[196:199], v148 offset:17408
	ds_read_b128 v[200:203], v148 offset:18432
	ds_read_b128 v[204:207], v148 offset:19456
	ds_read_b128 v[208:211], v148 offset:20480
	ds_read_b128 v[212:215], v148 offset:21504
	ds_read_b128 v[216:219], v148 offset:22528
	ds_read_b128 v[220:223], v148 offset:23552
	global_load_lds_dwordx4 v132, s[76:77]
	s_add_i32 m0, s0, 0x2000
	s_add_u32 s0, s76, 0x80000
	s_addc_u32 s1, s77, 0
	s_add_i32 s83, s84, s20
	global_load_lds_dwordx4 v136, s[76:77]
	s_mov_b32 m0, s83
	s_nop 0
	global_load_lds_dwordx4 v132, s[0:1]
	s_add_i32 m0, s83, 0x2000
	s_nop 0
	global_load_lds_dwordx4 v136, s[0:1]
	s_mov_b32 m0, s35
	s_nop 0
	global_load_lds_dwordx4 v130, s[78:79]
	s_mov_b32 m0, s37
	s_nop 0
	global_load_lds_dwordx4 v134, s[78:79]
	s_cmp_eq_u32 s101, 1
	s_cbranch_scc1 .Lrlx_qkv_1
	s_waitcnt vmcnt(8)
; #define PG8_STAGE(bufoff, gbase, voff) do { _Pragma("unroll") for (int _i = 0; _i < 2; ++_i) \
;         __builtin_amdgcn_global_load_lds((const unsigned*)((const char*)(gbase) + (voff)[_i]), (PG8_LAS unsigned*)(lds + (bufoff) + ldsw + _i * 8192), 16, 0, 0); } while (0)
; #define PG8_LDA(dst, b, h) do { _Pragma("unroll") for (int m = 0; m < 4; ++m) _Pragma("unroll") for (int k = 0; k < 2; ++k) dst[m][k] = *(const PG8_LAS bf16x8*)(lds + PG8_SA(b, h) + aoff + m * 2048 + k * 1024); } while (0)
; #define PG8_LDB(dst, b, h) do { _Pragma("unroll") for (int n = 0; n < 2; ++n) _Pragma("unroll") for (int k = 0; k < 2; ++k) dst[n][k] = *(const PG8_LAS bf16x8*)(lds + PG8_SB(b, h) + boff + n * 2048 + k * 1024); } while (0)
; #define PG8_WAIT_V(n) asm volatile("s_waitcnt vmcnt(" #n ")" ::: "memory")
; #define PG8_WAIT_L(n) asm volatile("s_waitcnt lgkmcnt(" #n ")" ::: "memory")
; #define PG8_BAR __builtin_amdgcn_s_barrier()
; #define PG8_SCHED __builtin_amdgcn_sched_barrier(0)
;     ...
;             PG8_WAIT_L(0); PG8_BAR; PG8_MMA(1, 0, At, B0); PG8_MMA(1, 1, At, B1); PG8_BAR; PG8_SCHED;
;             PG8_LDB(B0, 1, 0); PG8_LDB(B1, 1, 1); PG8_SCHED; PG8_LDA(At, 1, 0); PG8_STAGE(PG8_SA(0, 1), a2 + hstep, voffA);
;             PG8_WAIT_V(8); PG8_WAIT_L(0); PG8_BAR; PG8_MMA(0, 0, At, B0); PG8_MMA(0, 1, At, B1); PG8_BAR; PG8_SCHED;
;             PG8_LDA(At, 1, 1); PG8_STAGE(PG8_SB(1, 0), b3, voffB); PG8_STAGE(PG8_SB(1, 1), b3 + hstep, voffB); PG8_STAGE(PG8_SA(1, 0), a3, voffA);
.Lrlx_qkv_1_b:
	s_waitcnt lgkmcnt(0)
	s_setprio 1
	s_barrier
	v_mfma_f32_16x16x32_bf16 v[94:97], v[150:153], v[192:195], v[94:97]
	v_mfma_f32_16x16x32_bf16 v[94:97], v[154:157], v[196:199], v[94:97]
	v_mfma_f32_16x16x32_bf16 v[90:93], v[150:153], v[200:203], v[90:93]
	v_mfma_f32_16x16x32_bf16 v[90:93], v[154:157], v[204:207], v[90:93]
	v_mfma_f32_16x16x32_bf16 v[86:89], v[150:153], v[208:211], v[86:89]
	v_mfma_f32_16x16x32_bf16 v[86:89], v[154:157], v[212:215], v[86:89]
	v_mfma_f32_16x16x32_bf16 v[82:85], v[150:153], v[216:219], v[82:85]
	v_mfma_f32_16x16x32_bf16 v[82:85], v[154:157], v[220:223], v[82:85]
	v_mfma_f32_16x16x32_bf16 v[54:57], v[158:161], v[216:219], v[54:57]
	v_mfma_f32_16x16x32_bf16 v[54:57], v[162:165], v[220:223], v[54:57]
	v_mfma_f32_16x16x32_bf16 v[62:65], v[158:161], v[208:211], v[62:65]
	v_mfma_f32_16x16x32_bf16 v[62:65], v[162:165], v[212:215], v[62:65]
	v_mfma_f32_16x16x32_bf16 v[74:77], v[158:161], v[200:203], v[74:77]
	v_mfma_f32_16x16x32_bf16 v[74:77], v[162:165], v[204:207], v[74:77]
	v_mfma_f32_16x16x32_bf16 v[78:81], v[158:161], v[192:195], v[78:81]
	v_mfma_f32_16x16x32_bf16 v[78:81], v[162:165], v[196:199], v[78:81]
	v_mfma_f32_16x16x32_bf16 v[30:33], v[166:169], v[192:195], v[30:33]
	v_mfma_f32_16x16x32_bf16 v[30:33], v[172:175], v[196:199], v[30:33]
	v_mfma_f32_16x16x32_bf16 v[26:29], v[166:169], v[200:203], v[26:29]
	v_mfma_f32_16x16x32_bf16 v[26:29], v[172:175], v[204:207], v[26:29]
	v_mfma_f32_16x16x32_bf16 v[22:25], v[166:169], v[208:211], v[22:25]
	v_mfma_f32_16x16x32_bf16 v[22:25], v[172:175], v[212:215], v[22:25]
	v_mfma_f32_16x16x32_bf16 v[18:21], v[166:169], v[216:219], v[18:21]
	v_mfma_f32_16x16x32_bf16 v[18:21], v[172:175], v[220:223], v[18:21]
	v_mfma_f32_16x16x32_bf16 v[2:5], v[176:179], v[216:219], v[2:5]
	v_mfma_f32_16x16x32_bf16 v[2:5], v[188:191], v[220:223], v[2:5]
	v_mfma_f32_16x16x32_bf16 v[6:9], v[176:179], v[208:211], v[6:9]
	v_mfma_f32_16x16x32_bf16 v[6:9], v[188:191], v[212:215], v[6:9]
	v_mfma_f32_16x16x32_bf16 v[10:13], v[176:179], v[200:203], v[10:13]
	v_mfma_f32_16x16x32_bf16 v[10:13], v[188:191], v[204:207], v[10:13]
	v_mfma_f32_16x16x32_bf16 v[14:17], v[176:179], v[192:195], v[14:17]
	v_mfma_f32_16x16x32_bf16 v[14:17], v[188:191], v[196:199], v[14:17]
	s_barrier
	s_setprio 0
	s_add_i32 s83, 0, 0x18000
	s_add_i32 s84, 0, 0x1c000
	ds_read_b128 v[150:153], v180 offset:32768
	ds_read_b128 v[154:157], v180 offset:33792
	ds_read_b128 v[158:161], v180 offset:34816
	ds_read_b128 v[162:165], v180 offset:35840
	ds_read_b128 v[166:169], v180 offset:49152
	ds_read_b128 v[172:175], v180 offset:50176
	ds_read_b128 v[176:179], v180 offset:51200
	ds_read_b128 v[188:191], v180 offset:52224
	s_add_u32 s0, s78, 0x80000
	s_addc_u32 s1, s79, 0
	s_mov_b32 m0, s43
	ds_read_b128 v[192:195], v148 offset:32768
	ds_read_b128 v[196:199], v148 offset:33792
	ds_read_b128 v[200:203], v148 offset:34816
	ds_read_b128 v[204:207], v148 offset:35840
	ds_read_b128 v[208:211], v148 offset:36864
	ds_read_b128 v[212:215], v148 offset:37888
	ds_read_b128 v[216:219], v148 offset:38912
	ds_read_b128 v[220:223], v148 offset:39936
	global_load_lds_dwordx4 v130, s[0:1]
	s_mov_b32 m0, s44
	s_nop 0
	global_load_lds_dwordx4 v134, s[0:1]
	s_waitcnt vmcnt(8)
	s_waitcnt lgkmcnt(0)
	s_setprio 1
	s_barrier
	v_mfma_f32_16x16x32_bf16 v[126:129], v[150:153], v[192:195], v[126:129]
	v_mfma_f32_16x16x32_bf16 v[126:129], v[154:157], v[196:199], v[126:129]
	v_mfma_f32_16x16x32_bf16 v[122:125], v[150:153], v[200:203], v[122:125]
	v_mfma_f32_16x16x32_bf16 v[122:125], v[154:157], v[204:207], v[122:125]
	v_mfma_f32_16x16x32_bf16 v[118:121], v[150:153], v[208:211], v[118:121]
	v_mfma_f32_16x16x32_bf16 v[118:121], v[154:157], v[212:215], v[118:121]
	v_mfma_f32_16x16x32_bf16 v[114:117], v[150:153], v[216:219], v[114:117]
	v_mfma_f32_16x16x32_bf16 v[114:117], v[154:157], v[220:223], v[114:117]
	v_mfma_f32_16x16x32_bf16 v[98:101], v[158:161], v[216:219], v[98:101]
	v_mfma_f32_16x16x32_bf16 v[98:101], v[162:165], v[220:223], v[98:101]
	v_mfma_f32_16x16x32_bf16 v[102:105], v[158:161], v[208:211], v[102:105]
	v_mfma_f32_16x16x32_bf16 v[102:105], v[162:165], v[212:215], v[102:105]
	v_mfma_f32_16x16x32_bf16 v[106:109], v[158:161], v[200:203], v[106:109]
	v_mfma_f32_16x16x32_bf16 v[106:109], v[162:165], v[204:207], v[106:109]
	v_mfma_f32_16x16x32_bf16 v[110:113], v[158:161], v[192:195], v[110:113]
	v_mfma_f32_16x16x32_bf16 v[110:113], v[162:165], v[196:199], v[110:113]
	v_mfma_f32_16x16x32_bf16 v[70:73], v[166:169], v[192:195], v[70:73]
	v_mfma_f32_16x16x32_bf16 v[70:73], v[172:175], v[196:199], v[70:73]
	v_mfma_f32_16x16x32_bf16 v[66:69], v[166:169], v[200:203], v[66:69]
	v_mfma_f32_16x16x32_bf16 v[66:69], v[172:175], v[204:207], v[66:69]
	v_mfma_f32_16x16x32_bf16 v[58:61], v[166:169], v[208:211], v[58:61]
	v_mfma_f32_16x16x32_bf16 v[58:61], v[172:175], v[212:215], v[58:61]
	v_mfma_f32_16x16x32_bf16 v[46:49], v[166:169], v[216:219], v[46:49]
	v_mfma_f32_16x16x32_bf16 v[46:49], v[172:175], v[220:223], v[46:49]
	v_mfma_f32_16x16x32_bf16 v[34:37], v[176:179], v[216:219], v[34:37]
	v_mfma_f32_16x16x32_bf16 v[34:37], v[188:191], v[220:223], v[34:37]
	v_mfma_f32_16x16x32_bf16 v[38:41], v[176:179], v[208:211], v[38:41]
	v_mfma_f32_16x16x32_bf16 v[38:41], v[188:191], v[212:215], v[38:41]
	v_mfma_f32_16x16x32_bf16 v[42:45], v[176:179], v[200:203], v[42:45]
	v_mfma_f32_16x16x32_bf16 v[42:45], v[188:191], v[204:207], v[42:45]
	v_mfma_f32_16x16x32_bf16 v[50:53], v[176:179], v[192:195], v[50:53]
	v_mfma_f32_16x16x32_bf16 v[50:53], v[188:191], v[196:199], v[50:53]
	s_barrier
; #define PG8_STAGE(bufoff, gbase, voff) do { _Pragma("unroll") for (int _i = 0; _i < 2; ++_i) \
;         __builtin_amdgcn_global_load_lds((const unsigned*)((const char*)(gbase) + (voff)[_i]), (PG8_LAS unsigned*)(lds + (bufoff) + ldsw + _i * 8192), 16, 0, 0); } while (0)
; #define PG8_LDA(dst, b, h) do { _Pragma("unroll") for (int m = 0; m < 4; ++m) _Pragma("unroll") for (int k = 0; k < 2; ++k) dst[m][k] = *(const PG8_LAS bf16x8*)(lds + PG8_SA(b, h) + aoff + m * 2048 + k * 1024); } while (0)
; #define PG8_WAIT_V(n) asm volatile("s_waitcnt vmcnt(" #n ")" ::: "memory")
; #define PG8_WAIT_L(n) asm volatile("s_waitcnt lgkmcnt(" #n ")" ::: "memory")
; #define PG8_BAR __builtin_amdgcn_s_barrier()
; #define PG8_SCHED __builtin_amdgcn_sched_barrier(0)
;     ...
;             PG8_LDA(At, 1, 1); PG8_STAGE(PG8_SB(1, 0), b3, voffB); PG8_STAGE(PG8_SB(1, 1), b3 + hstep, voffB); PG8_STAGE(PG8_SA(1, 0), a3, voffA);
;             PG8_WAIT_V(8); PG8_WAIT_L(0); PG8_BAR; PG8_MMA(1, 0, At, B0); PG8_MMA(1, 1, At, B1); PG8_BAR; PG8_SCHED;
	s_setprio 0
	s_add_i32 s0, s83, s20
	s_mov_b32 m0, s0
	ds_read_b128 v[192:195], v148 offset:49152
	ds_read_b128 v[196:199], v148 offset:50176
	ds_read_b128 v[200:203], v148 offset:51200
	ds_read_b128 v[204:207], v148 offset:52224
	ds_read_b128 v[208:211], v148 offset:53248
	ds_read_b128 v[212:215], v148 offset:54272
	ds_read_b128 v[216:219], v148 offset:55296
	ds_read_b128 v[220:223], v148 offset:56320
	s_add_u32 s100, s76, 0x80
	s_addc_u32 s101, s77, 0
	global_load_lds_dwordx4 v132, s[100:101]
	s_add_i32 m0, s0, 0x2000
	s_add_u32 s0, s76, 0x80080
	s_addc_u32 s1, s77, 0
	s_add_i32 s76, s84, s20
	global_load_lds_dwordx4 v136, s[100:101]
	s_mov_b32 m0, s76
	s_nop 0
	global_load_lds_dwordx4 v132, s[0:1]
	s_add_i32 m0, s76, 0x2000
	s_nop 0
	global_load_lds_dwordx4 v136, s[0:1]
	s_mov_b32 m0, s48
	s_nop 0
	s_add_u32 s100, s78, 0x80
	s_addc_u32 s101, s79, 0
	global_load_lds_dwordx4 v130, s[100:101]
	s_mov_b32 m0, s49
	s_nop 0
	global_load_lds_dwordx4 v134, s[100:101]
	s_waitcnt vmcnt(8)
	s_waitcnt lgkmcnt(0)
	s_setprio 1
	s_barrier
	v_mfma_f32_16x16x32_bf16 v[94:97], v[150:153], v[192:195], v[94:97]
	v_mfma_f32_16x16x32_bf16 v[94:97], v[154:157], v[196:199], v[94:97]
	v_mfma_f32_16x16x32_bf16 v[90:93], v[150:153], v[200:203], v[90:93]
	v_mfma_f32_16x16x32_bf16 v[90:93], v[154:157], v[204:207], v[90:93]
	v_mfma_f32_16x16x32_bf16 v[86:89], v[150:153], v[208:211], v[86:89]
	v_mfma_f32_16x16x32_bf16 v[86:89], v[154:157], v[212:215], v[86:89]
	v_mfma_f32_16x16x32_bf16 v[82:85], v[150:153], v[216:219], v[82:85]
	v_mfma_f32_16x16x32_bf16 v[82:85], v[154:157], v[220:223], v[82:85]
	v_mfma_f32_16x16x32_bf16 v[54:57], v[158:161], v[216:219], v[54:57]
	v_mfma_f32_16x16x32_bf16 v[54:57], v[162:165], v[220:223], v[54:57]
	v_mfma_f32_16x16x32_bf16 v[62:65], v[158:161], v[208:211], v[62:65]
	v_mfma_f32_16x16x32_bf16 v[62:65], v[162:165], v[212:215], v[62:65]
	v_mfma_f32_16x16x32_bf16 v[74:77], v[158:161], v[200:203], v[74:77]
	v_mfma_f32_16x16x32_bf16 v[74:77], v[162:165], v[204:207], v[74:77]
	v_mfma_f32_16x16x32_bf16 v[78:81], v[158:161], v[192:195], v[78:81]
	v_mfma_f32_16x16x32_bf16 v[78:81], v[162:165], v[196:199], v[78:81]
	v_mfma_f32_16x16x32_bf16 v[30:33], v[166:169], v[192:195], v[30:33]
	v_mfma_f32_16x16x32_bf16 v[30:33], v[172:175], v[196:199], v[30:33]
	v_mfma_f32_16x16x32_bf16 v[26:29], v[166:169], v[200:203], v[26:29]
	v_mfma_f32_16x16x32_bf16 v[26:29], v[172:175], v[204:207], v[26:29]
	v_mfma_f32_16x16x32_bf16 v[22:25], v[166:169], v[208:211], v[22:25]
	v_mfma_f32_16x16x32_bf16 v[22:25], v[172:175], v[212:215], v[22:25]
	v_mfma_f32_16x16x32_bf16 v[18:21], v[166:169], v[216:219], v[18:21]
	v_mfma_f32_16x16x32_bf16 v[18:21], v[172:175], v[220:223], v[18:21]
	v_mfma_f32_16x16x32_bf16 v[2:5], v[176:179], v[216:219], v[2:5]
	v_mfma_f32_16x16x32_bf16 v[2:5], v[188:191], v[220:223], v[2:5]
	v_mfma_f32_16x16x32_bf16 v[6:9], v[176:179], v[208:211], v[6:9]
	v_mfma_f32_16x16x32_bf16 v[6:9], v[188:191], v[212:215], v[6:9]
	v_mfma_f32_16x16x32_bf16 v[10:13], v[176:179], v[200:203], v[10:13]
	v_mfma_f32_16x16x32_bf16 v[10:13], v[188:191], v[204:207], v[10:13]
	v_mfma_f32_16x16x32_bf16 v[14:17], v[176:179], v[192:195], v[14:17]
	v_mfma_f32_16x16x32_bf16 v[14:17], v[188:191], v[196:199], v[14:17]
	s_barrier
	s_setprio 0
	s_add_i32 s82, s82, 2
	s_add_u32 s74, s74, 0x100
	s_addc_u32 s75, s75, 0
	s_add_u32 s80, s80, 0x100
	s_addc_u32 s81, s81, 0
	s_cmp_gt_u32 s82, 29
	s_mov_b32 s101, 0
	s_cbranch_scc0 .LBB0_596
	s_branch .Lrlx_qkv_x

; #define PG8_BAR __builtin_amdgcn_s_barrier()
;     ...
;         }
;         unsigned long long tp0 = 0; if constexpr (TP == 1) tp0 = __builtin_amdgcn_s_memrealtime();
;         if constexpr (ALIGN_EPI) { if (wr == 0) PG8_BAR; }
.Lrlx_qkv_x:
	s_and_b64 vcc, exec, s[62:63]
	s_cbranch_vccz .LBB0_599
	s_barrier

;     __device__ __forceinline__ bool next(int i, Unit& v) const { if (i != 0) return false; v = u; return true; }
;     __host__ __device__ bool next(int i, Unit& u) const { const long L = (long)i * G + c; if (L >= lim) return false; unit_of((int)L, u); return true; }
;     ...
;         const bool has_next = S.next(ui + 1, nxt);
;         if constexpr (TP == 3) { if (ui > 0) tp_acc += __builtin_amdgcn_s_memrealtime() - tp3; }
;         const char* nA = has_next ? (const char*)g.A + (size_t)nxt.pm * tstep : cA; const char* nB = has_next ? (const char*)g.Bt + (size_t)nxt.pn * tstep : cB;
.LBB0_1163:
	s_cmp_lg_u32 s57, 0
	s_cselect_b32 s101, 1, 0
	s_add_i32 s56, s57, 1
	s_mul_i32 s0, s56, s26
	s_mul_hi_u32 s1, s56, s18
	s_add_i32 s1, s1, s0
	s_mul_i32 s0, s56, s18
	s_add_u32 s40, s0, s96
	s_addc_u32 s41, s1, s49
	v_mov_b64_e32 v[2:3], 0x3ff
	v_cmp_gt_i64_e32 vcc, s[40:41], v[2:3]
	v_cmp_lt_i64_e64 s[4:5], s[40:41], v[252:253]
	s_cbranch_vccnz .LBB0_1169
	s_ashr_i32 s0, s40, 31
	s_lshr_b32 s0, s0, 29
	s_add_i32 s0, s40, s0
	s_and_b32 s1, s0, -8
	s_sub_i32 s1, s40, s1
	s_cmp_gt_i32 s1, -1
	s_mov_b64 s[40:41], -1
	s_cbranch_scc0 .LBB0_1166
	s_lshl_b32 s66, s1, 7
	s_mov_b64 s[40:41], 0

; #define PG8_STAGE(bufoff, gbase, voff) do { _Pragma("unroll") for (int _i = 0; _i < 2; ++_i) \
;         __builtin_amdgcn_global_load_lds((const unsigned*)((const char*)(gbase) + (voff)[_i]), (PG8_LAS unsigned*)(lds + (bufoff) + ldsw + _i * 8192), 16, 0, 0); } while (0)
; #define PG8_LDA(dst, b, h) do { _Pragma("unroll") for (int m = 0; m < 4; ++m) _Pragma("unroll") for (int k = 0; k < 2; ++k) dst[m][k] = *(const PG8_LAS bf16x8*)(lds + PG8_SA(b, h) + aoff + m * 2048 + k * 1024); } while (0)
; #define PG8_LDB(dst, b, h) do { _Pragma("unroll") for (int n = 0; n < 2; ++n) _Pragma("unroll") for (int k = 0; k < 2; ++k) dst[n][k] = *(const PG8_LAS bf16x8*)(lds + PG8_SB(b, h) + boff + n * 2048 + k * 1024); } while (0)
; #define PG8_WAIT_L(n) asm volatile("s_waitcnt lgkmcnt(" #n ")" ::: "memory")
; #define PG8_WAIT_V_SEL(sel) asm volatile("s_cmp_eq_u32 %0, 0\n\ts_cbranch_scc1 .Lw8_%=\n\ts_waitcnt vmcnt(22)\n\ts_branch .Lwd_%=\n.Lw8_%=:\n\ts_waitcnt vmcnt(8)\n.Lwd_%=:" :: "s"(sel) : "memory", "scc")
; #define PG8_BAR __builtin_amdgcn_s_barrier()
; #define PG8_SCHED __builtin_amdgcn_sched_barrier(0)
;     ...
;         for (int t = 0; t < nt * KREP; t += 2) {
;             const bool last = (t == nt * KREP - 2);
;             const int t1w = KREP > 1 ? ((t + 1) & (nt - 1)) : t + 1, t2w = KREP > 1 ? ((t + 2) & (nt - 1)) : t + 2;
;             const char* a1 = cA + (size_t)t1w * kstep;
;             const char* a2 = last ? nA : cA + (size_t)t2w * kstep; const char* b2 = last ? nB : cB + (size_t)t2w * kstep;
;             const char* a3 = a2 + kstep; const char* b3 = b2 + kstep;
;             if (last && has_next) S.a_ready(nxt);
;             const int relax = __builtin_amdgcn_readfirstlane((MK_RELAXW && t == 0 && ui > 0) ? 1 : 0);
;             if constexpr (SP2) {
;             PG8_LDB(B0, 0, 0); PG8_LDB(B1, 0, 1); PG8_SCHED; PG8_LDA(At, 0, 0); PG8_STAGE(PG8_SA(1, 1), a1 + hstep, voffA);
;             PG8_WAIT_V_SEL(relax);
;             PG8_WAIT_L(0); PG8_BAR; PG8_MMA(0, 0, At, B0); PG8_MMA(0, 1, At, B1); PG8_BAR; PG8_SCHED;
;             PG8_LDA(At, 0, 1); PG8_STAGE(PG8_SB(0, 0), b2, voffB); PG8_STAGE(PG8_SB(0, 1), b2 + hstep, voffB); PG8_STAGE(PG8_SA(0, 0), a2, voffA);
;             PG8_WAIT_V_SEL(relax);
;             PG8_WAIT_L(0); PG8_BAR; PG8_MMA(1, 0, At, B0); PG8_MMA(1, 1, At, B1); PG8_BAR; PG8_SCHED;
.LBB0_1170:
	s_add_u32 s0, s78, 0xfff80080
	s_addc_u32 s1, s79, -1
	s_add_i32 s85, 0, 0x10000
	s_cmp_eq_u32 s84, 28
	s_cselect_b32 s83, s40, s1
	s_cselect_b32 s82, s41, s0
	s_cselect_b32 s81, s67, s77
	s_cselect_b32 s80, s69, s75
	s_add_i32 s86, 0, 0x14000
	ds_read_b128 v[90:93], v184
	ds_read_b128 v[94:97], v184 offset:1024
	ds_read_b128 v[98:101], v184 offset:2048
	ds_read_b128 v[102:105], v184 offset:3072
	ds_read_b128 v[146:149], v184 offset:16384
	ds_read_b128 v[150:153], v184 offset:17408
	ds_read_b128 v[154:157], v184 offset:18432
	ds_read_b128 v[158:161], v184 offset:19456
	s_add_i32 m0, s45, 0xc000
	ds_read_b128 v[162:165], v227
	ds_read_b128 v[166:169], v227 offset:1024
	ds_read_b128 v[188:191], v227 offset:2048
	ds_read_b128 v[192:195], v227 offset:3072
	ds_read_b128 v[196:199], v227 offset:4096
	ds_read_b128 v[200:203], v227 offset:5120
	ds_read_b128 v[204:207], v227 offset:6144
	ds_read_b128 v[208:211], v227 offset:7168
	global_load_lds_dwordx4 v178, s[78:79]
	s_add_i32 m0, s45, 0xe000
	s_nop 0
	global_load_lds_dwordx4 v180, s[78:79]
	s_cmp_eq_u32 s101, 1
	s_cbranch_scc1 .Lrlx_wo_0
	s_waitcnt vmcnt(8)
.Lrlx_wo_0_b:
	s_waitcnt lgkmcnt(0)
	s_setprio 1
	s_barrier
	v_mfma_f32_16x16x32_bf16 v[142:145], v[90:93], v[162:165], v[142:145]
	v_mfma_f32_16x16x32_bf16 v[142:145], v[94:97], v[166:169], v[142:145]
	v_mfma_f32_16x16x32_bf16 v[126:129], v[90:93], v[188:191], v[126:129]
	v_mfma_f32_16x16x32_bf16 v[126:129], v[94:97], v[192:195], v[126:129]
	v_mfma_f32_16x16x32_bf16 v[110:113], v[90:93], v[196:199], v[110:113]
	v_mfma_f32_16x16x32_bf16 v[110:113], v[94:97], v[200:203], v[110:113]
	v_mfma_f32_16x16x32_bf16 v[78:81], v[90:93], v[204:207], v[78:81]
	v_mfma_f32_16x16x32_bf16 v[78:81], v[94:97], v[208:211], v[78:81]
	v_mfma_f32_16x16x32_bf16 v[74:77], v[98:101], v[204:207], v[74:77]
	v_mfma_f32_16x16x32_bf16 v[74:77], v[102:105], v[208:211], v[74:77]
	v_mfma_f32_16x16x32_bf16 v[106:109], v[98:101], v[196:199], v[106:109]
	v_mfma_f32_16x16x32_bf16 v[106:109], v[102:105], v[200:203], v[106:109]
	v_mfma_f32_16x16x32_bf16 v[122:125], v[98:101], v[188:191], v[122:125]
	v_mfma_f32_16x16x32_bf16 v[122:125], v[102:105], v[192:195], v[122:125]
	v_mfma_f32_16x16x32_bf16 v[138:141], v[98:101], v[162:165], v[138:141]
	v_mfma_f32_16x16x32_bf16 v[138:141], v[102:105], v[166:169], v[138:141]
	v_mfma_f32_16x16x32_bf16 v[134:137], v[146:149], v[162:165], v[134:137]
	v_mfma_f32_16x16x32_bf16 v[134:137], v[150:153], v[166:169], v[134:137]
	v_mfma_f32_16x16x32_bf16 v[118:121], v[146:149], v[188:191], v[118:121]
	v_mfma_f32_16x16x32_bf16 v[118:121], v[150:153], v[192:195], v[118:121]
	v_mfma_f32_16x16x32_bf16 v[86:89], v[146:149], v[196:199], v[86:89]
	v_mfma_f32_16x16x32_bf16 v[86:89], v[150:153], v[200:203], v[86:89]
	v_mfma_f32_16x16x32_bf16 v[70:73], v[146:149], v[204:207], v[70:73]
	v_mfma_f32_16x16x32_bf16 v[70:73], v[150:153], v[208:211], v[70:73]
	v_mfma_f32_16x16x32_bf16 v[66:69], v[154:157], v[204:207], v[66:69]
	v_mfma_f32_16x16x32_bf16 v[66:69], v[158:161], v[208:211], v[66:69]
	v_mfma_f32_16x16x32_bf16 v[82:85], v[154:157], v[196:199], v[82:85]
	v_mfma_f32_16x16x32_bf16 v[82:85], v[158:161], v[200:203], v[82:85]
	v_mfma_f32_16x16x32_bf16 v[114:117], v[154:157], v[188:191], v[114:117]
	v_mfma_f32_16x16x32_bf16 v[114:117], v[158:161], v[192:195], v[114:117]
	v_mfma_f32_16x16x32_bf16 v[130:133], v[154:157], v[162:165], v[130:133]
	v_mfma_f32_16x16x32_bf16 v[130:133], v[158:161], v[166:169], v[130:133]
	s_barrier
	s_setprio 0
	s_add_i32 s0, s85, s33
	s_mov_b32 m0, s0
	ds_read_b128 v[162:165], v227 offset:16384
	ds_read_b128 v[166:169], v227 offset:17408
	ds_read_b128 v[188:191], v227 offset:18432
	ds_read_b128 v[192:195], v227 offset:19456
	ds_read_b128 v[196:199], v227 offset:20480
	ds_read_b128 v[200:203], v227 offset:21504
	ds_read_b128 v[204:207], v227 offset:22528
	ds_read_b128 v[208:211], v227 offset:23552
	global_load_lds_dwordx4 v182, s[80:81]
	s_add_i32 m0, s0, 0x2000
	s_add_u32 s0, s80, 0x80000
	s_addc_u32 s1, s81, 0
	s_add_i32 s85, s86, s33
	global_load_lds_dwordx4 v176, s[80:81]
	s_mov_b32 m0, s85
	s_nop 0
	global_load_lds_dwordx4 v182, s[0:1]
	s_add_i32 m0, s85, 0x2000
	s_nop 0
	global_load_lds_dwordx4 v176, s[0:1]
	s_mov_b32 m0, s45
	s_nop 0
	global_load_lds_dwordx4 v172, s[82:83]
	s_mov_b32 m0, s46
	s_nop 0
	global_load_lds_dwordx4 v174, s[82:83]
	s_cmp_eq_u32 s101, 1
	s_cbranch_scc1 .Lrlx_wo_1
	s_waitcnt vmcnt(8)
; #define PG8_STAGE(bufoff, gbase, voff) do { _Pragma("unroll") for (int _i = 0; _i < 2; ++_i) \
;         __builtin_amdgcn_global_load_lds((const unsigned*)((const char*)(gbase) + (voff)[_i]), (PG8_LAS unsigned*)(lds + (bufoff) + ldsw + _i * 8192), 16, 0, 0); } while (0)
; #define PG8_LDA(dst, b, h) do { _Pragma("unroll") for (int m = 0; m < 4; ++m) _Pragma("unroll") for (int k = 0; k < 2; ++k) dst[m][k] = *(const PG8_LAS bf16x8*)(lds + PG8_SA(b, h) + aoff + m * 2048 + k * 1024); } while (0)
; #define PG8_LDB(dst, b, h) do { _Pragma("unroll") for (int n = 0; n < 2; ++n) _Pragma("unroll") for (int k = 0; k < 2; ++k) dst[n][k] = *(const PG8_LAS bf16x8*)(lds + PG8_SB(b, h) + boff + n * 2048 + k * 1024); } while (0)
; #define PG8_WAIT_V(n) asm volatile("s_waitcnt vmcnt(" #n ")" ::: "memory")
; #define PG8_WAIT_L(n) asm volatile("s_waitcnt lgkmcnt(" #n ")" ::: "memory")
; #define PG8_BAR __builtin_amdgcn_s_barrier()
; #define PG8_SCHED __builtin_amdgcn_sched_barrier(0)
;     ...
;             PG8_WAIT_L(0); PG8_BAR; PG8_MMA(1, 0, At, B0); PG8_MMA(1, 1, At, B1); PG8_BAR; PG8_SCHED;
;             PG8_LDB(B0, 1, 0); PG8_LDB(B1, 1, 1); PG8_SCHED; PG8_LDA(At, 1, 0); PG8_STAGE(PG8_SA(0, 1), a2 + hstep, voffA);
;             PG8_WAIT_V(8); PG8_WAIT_L(0); PG8_BAR; PG8_MMA(0, 0, At, B0); PG8_MMA(0, 1, At, B1); PG8_BAR; PG8_SCHED;
;             PG8_LDA(At, 1, 1); PG8_STAGE(PG8_SB(1, 0), b3, voffB); PG8_STAGE(PG8_SB(1, 1), b3 + hstep, voffB); PG8_STAGE(PG8_SA(1, 0), a3, voffA);
.Lrlx_wo_1_b:
	s_waitcnt lgkmcnt(0)
	s_setprio 1
	s_barrier
	v_mfma_f32_16x16x32_bf16 v[62:65], v[90:93], v[162:165], v[62:65]
	v_mfma_f32_16x16x32_bf16 v[62:65], v[94:97], v[166:169], v[62:65]
	v_mfma_f32_16x16x32_bf16 v[46:49], v[90:93], v[188:191], v[46:49]
	v_mfma_f32_16x16x32_bf16 v[46:49], v[94:97], v[192:195], v[46:49]
	v_mfma_f32_16x16x32_bf16 v[30:33], v[90:93], v[196:199], v[30:33]
	v_mfma_f32_16x16x32_bf16 v[30:33], v[94:97], v[200:203], v[30:33]
	v_mfma_f32_16x16x32_bf16 v[14:17], v[90:93], v[204:207], v[14:17]
	v_mfma_f32_16x16x32_bf16 v[14:17], v[94:97], v[208:211], v[14:17]
	v_mfma_f32_16x16x32_bf16 v[10:13], v[98:101], v[204:207], v[10:13]
	v_mfma_f32_16x16x32_bf16 v[10:13], v[102:105], v[208:211], v[10:13]
	v_mfma_f32_16x16x32_bf16 v[26:29], v[98:101], v[196:199], v[26:29]
	v_mfma_f32_16x16x32_bf16 v[26:29], v[102:105], v[200:203], v[26:29]
	v_mfma_f32_16x16x32_bf16 v[42:45], v[98:101], v[188:191], v[42:45]
	v_mfma_f32_16x16x32_bf16 v[42:45], v[102:105], v[192:195], v[42:45]
	v_mfma_f32_16x16x32_bf16 v[58:61], v[98:101], v[162:165], v[58:61]
	v_mfma_f32_16x16x32_bf16 v[58:61], v[102:105], v[166:169], v[58:61]
	v_mfma_f32_16x16x32_bf16 v[54:57], v[146:149], v[162:165], v[54:57]
	v_mfma_f32_16x16x32_bf16 v[54:57], v[150:153], v[166:169], v[54:57]
	v_mfma_f32_16x16x32_bf16 v[38:41], v[146:149], v[188:191], v[38:41]
	v_mfma_f32_16x16x32_bf16 v[38:41], v[150:153], v[192:195], v[38:41]
	v_mfma_f32_16x16x32_bf16 v[22:25], v[146:149], v[196:199], v[22:25]
	v_mfma_f32_16x16x32_bf16 v[22:25], v[150:153], v[200:203], v[22:25]
	v_mfma_f32_16x16x32_bf16 v[6:9], v[146:149], v[204:207], v[6:9]
	v_mfma_f32_16x16x32_bf16 v[6:9], v[150:153], v[208:211], v[6:9]
	v_mfma_f32_16x16x32_bf16 v[2:5], v[154:157], v[204:207], v[2:5]
	v_mfma_f32_16x16x32_bf16 v[2:5], v[158:161], v[208:211], v[2:5]
	v_mfma_f32_16x16x32_bf16 v[18:21], v[154:157], v[196:199], v[18:21]
	v_mfma_f32_16x16x32_bf16 v[18:21], v[158:161], v[200:203], v[18:21]
	v_mfma_f32_16x16x32_bf16 v[34:37], v[154:157], v[188:191], v[34:37]
	v_mfma_f32_16x16x32_bf16 v[34:37], v[158:161], v[192:195], v[34:37]
	v_mfma_f32_16x16x32_bf16 v[50:53], v[154:157], v[162:165], v[50:53]
	v_mfma_f32_16x16x32_bf16 v[50:53], v[158:161], v[166:169], v[50:53]
	s_barrier
	s_setprio 0
	s_add_i32 s85, 0, 0x18000
	s_add_i32 s86, 0, 0x1c000
	ds_read_b128 v[90:93], v184 offset:32768
	ds_read_b128 v[94:97], v184 offset:33792
	ds_read_b128 v[98:101], v184 offset:34816
	ds_read_b128 v[102:105], v184 offset:35840
	ds_read_b128 v[146:149], v184 offset:49152
	ds_read_b128 v[150:153], v184 offset:50176
	ds_read_b128 v[154:157], v184 offset:51200
	ds_read_b128 v[158:161], v184 offset:52224
	s_add_u32 s0, s82, 0x80000
	s_addc_u32 s1, s83, 0
	s_mov_b32 m0, s47
	ds_read_b128 v[162:165], v227 offset:32768
	ds_read_b128 v[166:169], v227 offset:33792
	ds_read_b128 v[188:191], v227 offset:34816
	ds_read_b128 v[192:195], v227 offset:35840
	ds_read_b128 v[196:199], v227 offset:36864
	ds_read_b128 v[200:203], v227 offset:37888
	ds_read_b128 v[204:207], v227 offset:38912
	ds_read_b128 v[208:211], v227 offset:39936
	global_load_lds_dwordx4 v172, s[0:1]
	s_mov_b32 m0, s48
	s_nop 0
	global_load_lds_dwordx4 v174, s[0:1]
	s_waitcnt vmcnt(8)
	s_waitcnt lgkmcnt(0)
	s_setprio 1
	s_barrier
	v_mfma_f32_16x16x32_bf16 v[142:145], v[90:93], v[162:165], v[142:145]
	v_mfma_f32_16x16x32_bf16 v[142:145], v[94:97], v[166:169], v[142:145]
	v_mfma_f32_16x16x32_bf16 v[126:129], v[90:93], v[188:191], v[126:129]
	v_mfma_f32_16x16x32_bf16 v[126:129], v[94:97], v[192:195], v[126:129]
	v_mfma_f32_16x16x32_bf16 v[110:113], v[90:93], v[196:199], v[110:113]
	v_mfma_f32_16x16x32_bf16 v[110:113], v[94:97], v[200:203], v[110:113]
	v_mfma_f32_16x16x32_bf16 v[78:81], v[90:93], v[204:207], v[78:81]
	v_mfma_f32_16x16x32_bf16 v[78:81], v[94:97], v[208:211], v[78:81]
	v_mfma_f32_16x16x32_bf16 v[74:77], v[98:101], v[204:207], v[74:77]
	v_mfma_f32_16x16x32_bf16 v[74:77], v[102:105], v[208:211], v[74:77]
	v_mfma_f32_16x16x32_bf16 v[106:109], v[98:101], v[196:199], v[106:109]
	v_mfma_f32_16x16x32_bf16 v[106:109], v[102:105], v[200:203], v[106:109]
	v_mfma_f32_16x16x32_bf16 v[122:125], v[98:101], v[188:191], v[122:125]
	v_mfma_f32_16x16x32_bf16 v[122:125], v[102:105], v[192:195], v[122:125]
	v_mfma_f32_16x16x32_bf16 v[138:141], v[98:101], v[162:165], v[138:141]
	v_mfma_f32_16x16x32_bf16 v[138:141], v[102:105], v[166:169], v[138:141]
	v_mfma_f32_16x16x32_bf16 v[134:137], v[146:149], v[162:165], v[134:137]
	v_mfma_f32_16x16x32_bf16 v[134:137], v[150:153], v[166:169], v[134:137]
	v_mfma_f32_16x16x32_bf16 v[118:121], v[146:149], v[188:191], v[118:121]
	v_mfma_f32_16x16x32_bf16 v[118:121], v[150:153], v[192:195], v[118:121]
	v_mfma_f32_16x16x32_bf16 v[86:89], v[146:149], v[196:199], v[86:89]
	v_mfma_f32_16x16x32_bf16 v[86:89], v[150:153], v[200:203], v[86:89]
	v_mfma_f32_16x16x32_bf16 v[70:73], v[146:149], v[204:207], v[70:73]
	v_mfma_f32_16x16x32_bf16 v[70:73], v[150:153], v[208:211], v[70:73]
	v_mfma_f32_16x16x32_bf16 v[66:69], v[154:157], v[204:207], v[66:69]
	v_mfma_f32_16x16x32_bf16 v[66:69], v[158:161], v[208:211], v[66:69]
	v_mfma_f32_16x16x32_bf16 v[82:85], v[154:157], v[196:199], v[82:85]
	v_mfma_f32_16x16x32_bf16 v[82:85], v[158:161], v[200:203], v[82:85]
	v_mfma_f32_16x16x32_bf16 v[114:117], v[154:157], v[188:191], v[114:117]
	v_mfma_f32_16x16x32_bf16 v[114:117], v[158:161], v[192:195], v[114:117]
	v_mfma_f32_16x16x32_bf16 v[130:133], v[154:157], v[162:165], v[130:133]
	v_mfma_f32_16x16x32_bf16 v[130:133], v[158:161], v[166:169], v[130:133]
	s_barrier
; #define PG8_STAGE(bufoff, gbase, voff) do { _Pragma("unroll") for (int _i = 0; _i < 2; ++_i) \
;         __builtin_amdgcn_global_load_lds((const unsigned*)((const char*)(gbase) + (voff)[_i]), (PG8_LAS unsigned*)(lds + (bufoff) + ldsw + _i * 8192), 16, 0, 0); } while (0)
; #define PG8_LDA(dst, b, h) do { _Pragma("unroll") for (int m = 0; m < 4; ++m) _Pragma("unroll") for (int k = 0; k < 2; ++k) dst[m][k] = *(const PG8_LAS bf16x8*)(lds + PG8_SA(b, h) + aoff + m * 2048 + k * 1024); } while (0)
; #define PG8_WAIT_V(n) asm volatile("s_waitcnt vmcnt(" #n ")" ::: "memory")
; #define PG8_WAIT_L(n) asm volatile("s_waitcnt lgkmcnt(" #n ")" ::: "memory")
; #define PG8_BAR __builtin_amdgcn_s_barrier()
; #define PG8_SCHED __builtin_amdgcn_sched_barrier(0)
;     ...
;             PG8_LDA(At, 1, 1); PG8_STAGE(PG8_SB(1, 0), b3, voffB); PG8_STAGE(PG8_SB(1, 1), b3 + hstep, voffB); PG8_STAGE(PG8_SA(1, 0), a3, voffA);
;             PG8_WAIT_V(8); PG8_WAIT_L(0); PG8_BAR; PG8_MMA(1, 0, At, B0); PG8_MMA(1, 1, At, B1); PG8_BAR; PG8_SCHED;
	s_setprio 0
	s_add_i32 s0, s85, s33
	s_mov_b32 m0, s0
	ds_read_b128 v[162:165], v227 offset:49152
	ds_read_b128 v[166:169], v227 offset:50176
	ds_read_b128 v[188:191], v227 offset:51200
	ds_read_b128 v[192:195], v227 offset:52224
	ds_read_b128 v[196:199], v227 offset:53248
	ds_read_b128 v[200:203], v227 offset:54272
	ds_read_b128 v[204:207], v227 offset:55296
	ds_read_b128 v[208:211], v227 offset:56320
	s_add_u32 s100, s80, 0x80
	s_addc_u32 s101, s81, 0
	global_load_lds_dwordx4 v182, s[100:101]
	s_add_i32 m0, s0, 0x2000
	s_add_u32 s0, s80, 0x80080
	s_addc_u32 s1, s81, 0
	s_add_i32 s80, s86, s33
	global_load_lds_dwordx4 v176, s[100:101]
	s_mov_b32 m0, s80
	s_nop 0
	global_load_lds_dwordx4 v182, s[0:1]
	s_add_i32 m0, s80, 0x2000
	s_nop 0
	global_load_lds_dwordx4 v176, s[0:1]
	s_mov_b32 m0, s50
	s_nop 0
	s_add_u32 s100, s82, 0x80
	s_addc_u32 s101, s83, 0
	global_load_lds_dwordx4 v172, s[100:101]
	s_mov_b32 m0, s51
	s_nop 0
	global_load_lds_dwordx4 v174, s[100:101]
	s_waitcnt vmcnt(8)
	s_waitcnt lgkmcnt(0)
	s_setprio 1
	s_barrier
	v_mfma_f32_16x16x32_bf16 v[62:65], v[90:93], v[162:165], v[62:65]
	v_mfma_f32_16x16x32_bf16 v[62:65], v[94:97], v[166:169], v[62:65]
	v_mfma_f32_16x16x32_bf16 v[46:49], v[90:93], v[188:191], v[46:49]
	v_mfma_f32_16x16x32_bf16 v[46:49], v[94:97], v[192:195], v[46:49]
	v_mfma_f32_16x16x32_bf16 v[30:33], v[90:93], v[196:199], v[30:33]
	v_mfma_f32_16x16x32_bf16 v[30:33], v[94:97], v[200:203], v[30:33]
	v_mfma_f32_16x16x32_bf16 v[14:17], v[90:93], v[204:207], v[14:17]
	v_mfma_f32_16x16x32_bf16 v[14:17], v[94:97], v[208:211], v[14:17]
	v_mfma_f32_16x16x32_bf16 v[10:13], v[98:101], v[204:207], v[10:13]
	v_mfma_f32_16x16x32_bf16 v[10:13], v[102:105], v[208:211], v[10:13]
	v_mfma_f32_16x16x32_bf16 v[26:29], v[98:101], v[196:199], v[26:29]
	v_mfma_f32_16x16x32_bf16 v[26:29], v[102:105], v[200:203], v[26:29]
	v_mfma_f32_16x16x32_bf16 v[42:45], v[98:101], v[188:191], v[42:45]
	v_mfma_f32_16x16x32_bf16 v[42:45], v[102:105], v[192:195], v[42:45]
	v_mfma_f32_16x16x32_bf16 v[58:61], v[98:101], v[162:165], v[58:61]
	v_mfma_f32_16x16x32_bf16 v[58:61], v[102:105], v[166:169], v[58:61]
	v_mfma_f32_16x16x32_bf16 v[54:57], v[146:149], v[162:165], v[54:57]
	v_mfma_f32_16x16x32_bf16 v[54:57], v[150:153], v[166:169], v[54:57]
	v_mfma_f32_16x16x32_bf16 v[38:41], v[146:149], v[188:191], v[38:41]
	v_mfma_f32_16x16x32_bf16 v[38:41], v[150:153], v[192:195], v[38:41]
	v_mfma_f32_16x16x32_bf16 v[22:25], v[146:149], v[196:199], v[22:25]
	v_mfma_f32_16x16x32_bf16 v[22:25], v[150:153], v[200:203], v[22:25]
	v_mfma_f32_16x16x32_bf16 v[6:9], v[146:149], v[204:207], v[6:9]
	v_mfma_f32_16x16x32_bf16 v[6:9], v[150:153], v[208:211], v[6:9]
	v_mfma_f32_16x16x32_bf16 v[2:5], v[154:157], v[204:207], v[2:5]
	v_mfma_f32_16x16x32_bf16 v[2:5], v[158:161], v[208:211], v[2:5]
	v_mfma_f32_16x16x32_bf16 v[18:21], v[154:157], v[196:199], v[18:21]
	v_mfma_f32_16x16x32_bf16 v[18:21], v[158:161], v[200:203], v[18:21]
	v_mfma_f32_16x16x32_bf16 v[34:37], v[154:157], v[188:191], v[34:37]
	v_mfma_f32_16x16x32_bf16 v[34:37], v[158:161], v[192:195], v[34:37]
	v_mfma_f32_16x16x32_bf16 v[50:53], v[154:157], v[162:165], v[50:53]
	v_mfma_f32_16x16x32_bf16 v[50:53], v[158:161], v[166:169], v[50:53]
	s_barrier
	s_setprio 0
	s_add_i32 s84, s84, 2
	s_add_u32 s78, s78, 0x100
	s_addc_u32 s79, s79, 0
	s_add_u32 s75, s75, 0x100
	s_addc_u32 s77, s77, 0
	s_cmp_gt_u32 s84, 29
	s_mov_b32 s101, 0
	s_cbranch_scc0 .LBB0_1170
	s_branch .Lrlx_wo_x

;     __device__ __forceinline__ bool next(int i, Unit& v) const { if (i != 0) return false; v = u; return true; }
;     __host__ __device__ bool next(int i, Unit& u) const { const long L = (long)i * G + c; if (L >= lim) return false; unit_of((int)L, u); return true; }
;     ...
;         const bool has_next = S.next(ui + 1, nxt);
;         if constexpr (TP == 3) { if (ui > 0) tp_acc += __builtin_amdgcn_s_memrealtime() - tp3; }
;         const char* nA = has_next ? (const char*)g.A + (size_t)nxt.pm * tstep : cA; const char* nB = has_next ? (const char*)g.Bt + (size_t)nxt.pn * tstep : cB;
.LBB0_1324:
	s_cmp_lg_u32 s11, 0
	s_cselect_b32 s101, 1, 0
	s_add_i32 s58, s11, 1
	s_mul_i32 s0, s58, s35
	s_mul_hi_u32 s8, s58, s30
	s_add_i32 s8, s8, s0
	s_mul_i32 s0, s58, s30
	s_add_u32 s40, s0, s43
	s_addc_u32 s41, s8, s18
	v_mov_b64_e32 v[2:3], 0x1580
	v_cmp_lt_i64_e64 s[8:9], s[40:41], v[2:3]
	v_mov_b64_e32 v[2:3], 0x157f
	v_cmp_gt_i64_e32 vcc, s[40:41], v[2:3]
	s_cbranch_vccnz .LBB0_1326
	s_ashr_i32 s0, s40, 31
	s_lshr_b32 s0, s0, 29
	s_add_i32 s0, s40, s0
	s_ashr_i32 s41, s0, 3
	s_and_b32 s0, s0, -8
	s_sub_i32 s0, s40, s0
	s_cmp_lt_i32 s0, 0
	s_movk_i32 s19, 0x2b1
	s_cselect_b32 s40, s19, 0x2b0
	s_mul_i32 s0, s0, s40
	s_add_i32 s0, s0, s41
	s_mul_hi_i32 s40, s0, 0x2fa0be83
	s_lshr_b32 s41, s40, 31
	s_ashr_i32 s40, s40, 5
	s_add_i32 s40, s40, s41
	s_lshl_b32 s41, s40, 2
	s_sub_i32 s59, 0x80, s41
	s_min_i32 s59, s59, 4
	s_abs_i32 s64, s59
	v_cvt_f32_u32_e32 v2, s64
	s_sub_i32 s66, 0, s64
	s_mulk_i32 s40, 0xac
	s_sub_i32 s0, s0, s40
	v_rcp_iflag_f32_e32 v2, v2
	s_abs_i32 s40, s0
	s_xor_b32 s65, s0, s59
	s_ashr_i32 s65, s65, 31
	v_mul_f32_e32 v2, 0x4f7ffffe, v2
	v_cvt_u32_f32_e32 v2, v2
	s_nop 0
	v_readfirstlane_b32 s67, v2
	s_mul_i32 s66, s66, s67
	s_mul_hi_u32 s66, s67, s66
	s_add_i32 s67, s67, s66
	s_mul_hi_u32 s66, s40, s67
	s_mul_i32 s67, s66, s64
	s_sub_i32 s40, s40, s67
	s_add_i32 s86, s66, 1
	s_sub_i32 s67, s40, s64
	s_cmp_ge_u32 s40, s64
	s_cselect_b32 s66, s86, s66
	s_cselect_b32 s40, s67, s40
	s_add_i32 s67, s66, 1
	s_cmp_ge_u32 s40, s64
	s_cselect_b32 s40, s67, s66
	s_xor_b32 s40, s40, s65
	s_sub_i32 s86, s40, s65
	s_mul_i32 s40, s86, s59
	s_sub_i32 s0, s0, s40
	s_add_i32 s88, s41, s0

;     __device__ __forceinline__ bool next(int i, Unit& v) const { if (i != 0) return false; v = u; return true; }
;     __host__ __device__ bool next(int i, Unit& u) const { const long L = (long)i * G + c; if (L >= lim) return false; unit_of((int)L, u); return true; }
;     ...
;         const bool has_next = S.next(ui + 1, nxt);
;         if constexpr (TP == 3) { if (ui > 0) tp_acc += __builtin_amdgcn_s_memrealtime() - tp3; }
;         const char* nA = has_next ? (const char*)g.A + (size_t)nxt.pm * tstep : cA; const char* nB = has_next ? (const char*)g.Bt + (size_t)nxt.pn * tstep : cB;
.LBB0_1637:
	s_cmp_lg_u32 s35, 0
	s_cselect_b32 s101, 1, 0
	s_add_i32 s20, s35, 1
	s_mul_i32 s0, s20, s26
	s_mul_hi_u32 s1, s20, s23
	s_add_i32 s1, s1, s0
	s_mul_i32 s0, s20, s23
	s_add_u32 s6, s0, s43
	s_addc_u32 s7, s1, s95
	v_mov_b64_e32 v[2:3], 0x3ff
	v_cmp_gt_i64_e32 vcc, s[6:7], v[2:3]
	v_cmp_lt_i64_e64 s[0:1], s[6:7], v[252:253]
	s_cbranch_vccnz .LBB0_1643
	s_ashr_i32 s7, s6, 31
	s_lshr_b32 s7, s7, 29
	s_add_i32 s24, s6, s7
	s_and_b32 s7, s24, -8
	s_sub_i32 s33, s6, s7
	s_cmp_gt_i32 s33, -1
	s_mov_b64 s[6:7], -1
	s_cbranch_scc0 .LBB0_1640
	s_lshl_b32 s37, s33, 7
	s_mov_b64 s[6:7], 0

; #define PG8_STAGE(bufoff, gbase, voff) do { _Pragma("unroll") for (int _i = 0; _i < 2; ++_i) \
;         __builtin_amdgcn_global_load_lds((const unsigned*)((const char*)(gbase) + (voff)[_i]), (PG8_LAS unsigned*)(lds + (bufoff) + ldsw + _i * 8192), 16, 0, 0); } while (0)
; #define PG8_LDA(dst, b, h) do { _Pragma("unroll") for (int m = 0; m < 4; ++m) _Pragma("unroll") for (int k = 0; k < 2; ++k) dst[m][k] = *(const PG8_LAS bf16x8*)(lds + PG8_SA(b, h) + aoff + m * 2048 + k * 1024); } while (0)
; #define PG8_LDB(dst, b, h) do { _Pragma("unroll") for (int n = 0; n < 2; ++n) _Pragma("unroll") for (int k = 0; k < 2; ++k) dst[n][k] = *(const PG8_LAS bf16x8*)(lds + PG8_SB(b, h) + boff + n * 2048 + k * 1024); } while (0)
; #define PG8_WAIT_L(n) asm volatile("s_waitcnt lgkmcnt(" #n ")" ::: "memory")
; #define PG8_WAIT_V_SEL(sel) asm volatile("s_cmp_eq_u32 %0, 0\n\ts_cbranch_scc1 .Lw8_%=\n\ts_waitcnt vmcnt(22)\n\ts_branch .Lwd_%=\n.Lw8_%=:\n\ts_waitcnt vmcnt(8)\n.Lwd_%=:" :: "s"(sel) : "memory", "scc")
; #define PG8_BAR __builtin_amdgcn_s_barrier()
; #define PG8_SCHED __builtin_amdgcn_sched_barrier(0)
;     ...
;         for (int t = 0; t < nt * KREP; t += 2) {
;             const bool last = (t == nt * KREP - 2);
;             const int t1w = KREP > 1 ? ((t + 1) & (nt - 1)) : t + 1, t2w = KREP > 1 ? ((t + 2) & (nt - 1)) : t + 2;
;             const char* a1 = cA + (size_t)t1w * kstep;
;             const char* a2 = last ? nA : cA + (size_t)t2w * kstep; const char* b2 = last ? nB : cB + (size_t)t2w * kstep;
;             const char* a3 = a2 + kstep; const char* b3 = b2 + kstep;
;             if (last && has_next) S.a_ready(nxt);
;             const int relax = __builtin_amdgcn_readfirstlane((MK_RELAXW && t == 0 && ui > 0) ? 1 : 0);
;             if constexpr (SP2) {
;             PG8_LDB(B0, 0, 0); PG8_LDB(B1, 0, 1); PG8_SCHED; PG8_LDA(At, 0, 0); PG8_STAGE(PG8_SA(1, 1), a1 + hstep, voffA);
;             PG8_WAIT_V_SEL(relax);
;             PG8_WAIT_L(0); PG8_BAR; PG8_MMA(0, 0, At, B0); PG8_MMA(0, 1, At, B1); PG8_BAR; PG8_SCHED;
;             PG8_LDA(At, 0, 1); PG8_STAGE(PG8_SB(0, 0), b2, voffB); PG8_STAGE(PG8_SB(0, 1), b2 + hstep, voffB); PG8_STAGE(PG8_SA(0, 0), a2, voffA);
;             PG8_WAIT_V_SEL(relax);
.LBB0_1648:
	s_add_u32 s10, s8, 0x100
	s_addc_u32 s11, s9, 0
	s_add_i32 s46, 0, 0x10000
	s_cmpk_eq_i32 s45, 0x52
	s_cselect_b32 s41, s1, s11
	s_cselect_b32 s40, s0, s10
	s_cselect_b32 s81, s79, s44
	s_cselect_b32 s80, s78, s37
	s_add_i32 s47, 0, 0x14000
	ds_read_b128 v[58:61], v206
	ds_read_b128 v[62:65], v206 offset:1024
	ds_read_b128 v[74:77], v206 offset:2048
	ds_read_b128 v[78:81], v206 offset:3072
	ds_read_b128 v[130:133], v206 offset:16384
	ds_read_b128 v[142:145], v206 offset:17408
	ds_read_b128 v[154:157], v206 offset:18432
	ds_read_b128 v[158:161], v206 offset:19456
	s_add_i32 m0, s91, 0xc000
	ds_read_b128 v[162:165], v246
	ds_read_b128 v[166:169], v246 offset:1024
	ds_read_b128 v[170:173], v246 offset:2048
	ds_read_b128 v[174:177], v246 offset:3072
	ds_read_b128 v[184:187], v246 offset:4096
	ds_read_b128 v[194:197], v246 offset:5120
	ds_read_b128 v[198:201], v246 offset:6144
	ds_read_b128 v[202:205], v246 offset:7168
	global_load_lds_dwordx4 v190, s[8:9]
	s_add_i32 m0, s91, 0xe000
	s_nop 0
	global_load_lds_dwordx4 v192, s[8:9]
	s_cmp_eq_u32 s101, 1
	s_cbranch_scc1 .Lrlx_f2_0
	s_waitcnt vmcnt(8)
.Lrlx_f2_0_b:
	s_waitcnt lgkmcnt(0)
	s_setprio 1
	s_barrier
	v_mfma_f32_16x16x32_bf16 v[150:153], v[58:61], v[162:165], v[150:153]
	v_mfma_f32_16x16x32_bf16 v[150:153], v[62:65], v[166:169], v[150:153]
	v_mfma_f32_16x16x32_bf16 v[126:129], v[58:61], v[170:173], v[126:129]
	v_mfma_f32_16x16x32_bf16 v[126:129], v[62:65], v[174:177], v[126:129]
	v_mfma_f32_16x16x32_bf16 v[110:113], v[58:61], v[184:187], v[110:113]
	v_mfma_f32_16x16x32_bf16 v[110:113], v[62:65], v[194:197], v[110:113]
	v_mfma_f32_16x16x32_bf16 v[94:97], v[58:61], v[198:201], v[94:97]
	v_mfma_f32_16x16x32_bf16 v[94:97], v[62:65], v[202:205], v[94:97]
	v_mfma_f32_16x16x32_bf16 v[90:93], v[74:77], v[198:201], v[90:93]
	v_mfma_f32_16x16x32_bf16 v[90:93], v[78:81], v[202:205], v[90:93]
	v_mfma_f32_16x16x32_bf16 v[106:109], v[74:77], v[184:187], v[106:109]
	v_mfma_f32_16x16x32_bf16 v[106:109], v[78:81], v[194:197], v[106:109]
	v_mfma_f32_16x16x32_bf16 v[122:125], v[74:77], v[170:173], v[122:125]
	v_mfma_f32_16x16x32_bf16 v[122:125], v[78:81], v[174:177], v[122:125]
	v_mfma_f32_16x16x32_bf16 v[146:149], v[74:77], v[162:165], v[146:149]
	v_mfma_f32_16x16x32_bf16 v[146:149], v[78:81], v[166:169], v[146:149]
	v_mfma_f32_16x16x32_bf16 v[138:141], v[130:133], v[162:165], v[138:141]
	v_mfma_f32_16x16x32_bf16 v[138:141], v[142:145], v[166:169], v[138:141]
	v_mfma_f32_16x16x32_bf16 v[118:121], v[130:133], v[170:173], v[118:121]
	v_mfma_f32_16x16x32_bf16 v[118:121], v[142:145], v[174:177], v[118:121]
	v_mfma_f32_16x16x32_bf16 v[102:105], v[130:133], v[184:187], v[102:105]
	v_mfma_f32_16x16x32_bf16 v[102:105], v[142:145], v[194:197], v[102:105]
	v_mfma_f32_16x16x32_bf16 v[86:89], v[130:133], v[198:201], v[86:89]
	v_mfma_f32_16x16x32_bf16 v[86:89], v[142:145], v[202:205], v[86:89]
	v_mfma_f32_16x16x32_bf16 v[82:85], v[154:157], v[198:201], v[82:85]
	v_mfma_f32_16x16x32_bf16 v[82:85], v[158:161], v[202:205], v[82:85]
	v_mfma_f32_16x16x32_bf16 v[98:101], v[154:157], v[184:187], v[98:101]
	v_mfma_f32_16x16x32_bf16 v[98:101], v[158:161], v[194:197], v[98:101]
	v_mfma_f32_16x16x32_bf16 v[114:117], v[154:157], v[170:173], v[114:117]
	v_mfma_f32_16x16x32_bf16 v[114:117], v[158:161], v[174:177], v[114:117]
	v_mfma_f32_16x16x32_bf16 v[134:137], v[154:157], v[162:165], v[134:137]
	v_mfma_f32_16x16x32_bf16 v[134:137], v[158:161], v[166:169], v[134:137]
	s_barrier
	s_setprio 0
	s_add_i32 s8, s46, s90
	s_mov_b32 m0, s8
	ds_read_b128 v[162:165], v246 offset:16384
	ds_read_b128 v[166:169], v246 offset:17408
	ds_read_b128 v[170:173], v246 offset:18432
	ds_read_b128 v[174:177], v246 offset:19456
	ds_read_b128 v[184:187], v246 offset:20480
	ds_read_b128 v[194:197], v246 offset:21504
	ds_read_b128 v[198:201], v246 offset:22528
	ds_read_b128 v[202:205], v246 offset:23552
	global_load_lds_dwordx4 v182, s[80:81]
	s_add_i32 m0, s8, 0x2000
	s_add_u32 s8, s80, 0x158000
	s_addc_u32 s9, s81, 0
	s_add_i32 s46, s47, s90
	global_load_lds_dwordx4 v188, s[80:81]
	s_mov_b32 m0, s46
	s_nop 0
	global_load_lds_dwordx4 v182, s[8:9]
	s_add_i32 m0, s46, 0x2000
	s_nop 0
	global_load_lds_dwordx4 v188, s[8:9]
	s_mov_b32 m0, s91
	s_nop 0
	global_load_lds_dwordx4 v178, s[40:41]
	s_mov_b32 m0, s92
	s_nop 0
	global_load_lds_dwordx4 v180, s[40:41]
	s_cmp_eq_u32 s101, 1
	s_cbranch_scc1 .Lrlx_f2_1
	s_waitcnt vmcnt(8)
; #define PG8_STAGE(bufoff, gbase, voff) do { _Pragma("unroll") for (int _i = 0; _i < 2; ++_i) \
;         __builtin_amdgcn_global_load_lds((const unsigned*)((const char*)(gbase) + (voff)[_i]), (PG8_LAS unsigned*)(lds + (bufoff) + ldsw + _i * 8192), 16, 0, 0); } while (0)
; #define PG8_LDA(dst, b, h) do { _Pragma("unroll") for (int m = 0; m < 4; ++m) _Pragma("unroll") for (int k = 0; k < 2; ++k) dst[m][k] = *(const PG8_LAS bf16x8*)(lds + PG8_SA(b, h) + aoff + m * 2048 + k * 1024); } while (0)
; #define PG8_LDB(dst, b, h) do { _Pragma("unroll") for (int n = 0; n < 2; ++n) _Pragma("unroll") for (int k = 0; k < 2; ++k) dst[n][k] = *(const PG8_LAS bf16x8*)(lds + PG8_SB(b, h) + boff + n * 2048 + k * 1024); } while (0)
; #define PG8_WAIT_V(n) asm volatile("s_waitcnt vmcnt(" #n ")" ::: "memory")
; #define PG8_WAIT_L(n) asm volatile("s_waitcnt lgkmcnt(" #n ")" ::: "memory")
; #define PG8_WAIT_V_SEL(sel) asm volatile("s_cmp_eq_u32 %0, 0\n\ts_cbranch_scc1 .Lw8_%=\n\ts_waitcnt vmcnt(22)\n\ts_branch .Lwd_%=\n.Lw8_%=:\n\ts_waitcnt vmcnt(8)\n.Lwd_%=:" :: "s"(sel) : "memory", "scc")
; #define PG8_BAR __builtin_amdgcn_s_barrier()
; #define PG8_SCHED __builtin_amdgcn_sched_barrier(0)
;     ...
;             PG8_WAIT_V_SEL(relax);
;             PG8_WAIT_L(0); PG8_BAR; PG8_MMA(1, 0, At, B0); PG8_MMA(1, 1, At, B1); PG8_BAR; PG8_SCHED;
;             PG8_LDB(B0, 1, 0); PG8_LDB(B1, 1, 1); PG8_SCHED; PG8_LDA(At, 1, 0); PG8_STAGE(PG8_SA(0, 1), a2 + hstep, voffA);
;             PG8_WAIT_V(8); PG8_WAIT_L(0); PG8_BAR; PG8_MMA(0, 0, At, B0); PG8_MMA(0, 1, At, B1); PG8_BAR; PG8_SCHED;
.Lrlx_f2_1_b:
	s_waitcnt lgkmcnt(0)
	s_setprio 1
	s_barrier
	v_mfma_f32_16x16x32_bf16 v[70:73], v[58:61], v[162:165], v[70:73]
	v_mfma_f32_16x16x32_bf16 v[70:73], v[62:65], v[166:169], v[70:73]
	v_mfma_f32_16x16x32_bf16 v[46:49], v[58:61], v[170:173], v[46:49]
	v_mfma_f32_16x16x32_bf16 v[46:49], v[62:65], v[174:177], v[46:49]
	v_mfma_f32_16x16x32_bf16 v[30:33], v[58:61], v[184:187], v[30:33]
	v_mfma_f32_16x16x32_bf16 v[30:33], v[62:65], v[194:197], v[30:33]
	v_mfma_f32_16x16x32_bf16 v[14:17], v[58:61], v[198:201], v[14:17]
	v_mfma_f32_16x16x32_bf16 v[14:17], v[62:65], v[202:205], v[14:17]
	v_mfma_f32_16x16x32_bf16 v[10:13], v[74:77], v[198:201], v[10:13]
	v_mfma_f32_16x16x32_bf16 v[10:13], v[78:81], v[202:205], v[10:13]
	v_mfma_f32_16x16x32_bf16 v[26:29], v[74:77], v[184:187], v[26:29]
	v_mfma_f32_16x16x32_bf16 v[26:29], v[78:81], v[194:197], v[26:29]
	v_mfma_f32_16x16x32_bf16 v[42:45], v[74:77], v[170:173], v[42:45]
	v_mfma_f32_16x16x32_bf16 v[42:45], v[78:81], v[174:177], v[42:45]
	v_mfma_f32_16x16x32_bf16 v[66:69], v[74:77], v[162:165], v[66:69]
	v_mfma_f32_16x16x32_bf16 v[66:69], v[78:81], v[166:169], v[66:69]
	v_mfma_f32_16x16x32_bf16 v[54:57], v[130:133], v[162:165], v[54:57]
	v_mfma_f32_16x16x32_bf16 v[54:57], v[142:145], v[166:169], v[54:57]
	v_mfma_f32_16x16x32_bf16 v[38:41], v[130:133], v[170:173], v[38:41]
	v_mfma_f32_16x16x32_bf16 v[38:41], v[142:145], v[174:177], v[38:41]
	v_mfma_f32_16x16x32_bf16 v[22:25], v[130:133], v[184:187], v[22:25]
	v_mfma_f32_16x16x32_bf16 v[22:25], v[142:145], v[194:197], v[22:25]
	v_mfma_f32_16x16x32_bf16 v[6:9], v[130:133], v[198:201], v[6:9]
	v_mfma_f32_16x16x32_bf16 v[6:9], v[142:145], v[202:205], v[6:9]
	v_mfma_f32_16x16x32_bf16 v[2:5], v[154:157], v[198:201], v[2:5]
	v_mfma_f32_16x16x32_bf16 v[2:5], v[158:161], v[202:205], v[2:5]
	v_mfma_f32_16x16x32_bf16 v[18:21], v[154:157], v[184:187], v[18:21]
	v_mfma_f32_16x16x32_bf16 v[18:21], v[158:161], v[194:197], v[18:21]
	v_mfma_f32_16x16x32_bf16 v[34:37], v[154:157], v[170:173], v[34:37]
	v_mfma_f32_16x16x32_bf16 v[34:37], v[158:161], v[174:177], v[34:37]
	v_mfma_f32_16x16x32_bf16 v[50:53], v[154:157], v[162:165], v[50:53]
	v_mfma_f32_16x16x32_bf16 v[50:53], v[158:161], v[166:169], v[50:53]
	s_barrier
	s_setprio 0
	s_add_i32 s46, 0, 0x18000
	s_add_i32 s47, 0, 0x1c000
	ds_read_b128 v[58:61], v206 offset:32768
	ds_read_b128 v[62:65], v206 offset:33792
	ds_read_b128 v[74:77], v206 offset:34816
	ds_read_b128 v[78:81], v206 offset:35840
	ds_read_b128 v[130:133], v206 offset:49152
	ds_read_b128 v[142:145], v206 offset:50176
	ds_read_b128 v[154:157], v206 offset:51200
	ds_read_b128 v[158:161], v206 offset:52224
	s_add_u32 s8, s40, 0x158000
	s_addc_u32 s9, s41, 0
	s_mov_b32 m0, s93
	ds_read_b128 v[162:165], v246 offset:32768
	ds_read_b128 v[166:169], v246 offset:33792
	ds_read_b128 v[170:173], v246 offset:34816
	ds_read_b128 v[174:177], v246 offset:35840
	ds_read_b128 v[184:187], v246 offset:36864
	ds_read_b128 v[194:197], v246 offset:37888
	ds_read_b128 v[198:201], v246 offset:38912
	ds_read_b128 v[202:205], v246 offset:39936
	global_load_lds_dwordx4 v178, s[8:9]
	s_mov_b32 m0, s94
	s_nop 0
	global_load_lds_dwordx4 v180, s[8:9]
	s_waitcnt vmcnt(8)
	s_waitcnt lgkmcnt(0)
	s_setprio 1
	s_barrier
	v_mfma_f32_16x16x32_bf16 v[150:153], v[58:61], v[162:165], v[150:153]
	v_mfma_f32_16x16x32_bf16 v[150:153], v[62:65], v[166:169], v[150:153]
	v_mfma_f32_16x16x32_bf16 v[126:129], v[58:61], v[170:173], v[126:129]
	v_mfma_f32_16x16x32_bf16 v[126:129], v[62:65], v[174:177], v[126:129]
	v_mfma_f32_16x16x32_bf16 v[110:113], v[58:61], v[184:187], v[110:113]
	v_mfma_f32_16x16x32_bf16 v[110:113], v[62:65], v[194:197], v[110:113]
	v_mfma_f32_16x16x32_bf16 v[94:97], v[58:61], v[198:201], v[94:97]
	v_mfma_f32_16x16x32_bf16 v[94:97], v[62:65], v[202:205], v[94:97]
	v_mfma_f32_16x16x32_bf16 v[90:93], v[74:77], v[198:201], v[90:93]
	v_mfma_f32_16x16x32_bf16 v[90:93], v[78:81], v[202:205], v[90:93]
	v_mfma_f32_16x16x32_bf16 v[106:109], v[74:77], v[184:187], v[106:109]
	v_mfma_f32_16x16x32_bf16 v[106:109], v[78:81], v[194:197], v[106:109]
	v_mfma_f32_16x16x32_bf16 v[122:125], v[74:77], v[170:173], v[122:125]
	v_mfma_f32_16x16x32_bf16 v[122:125], v[78:81], v[174:177], v[122:125]
	v_mfma_f32_16x16x32_bf16 v[146:149], v[74:77], v[162:165], v[146:149]
	v_mfma_f32_16x16x32_bf16 v[146:149], v[78:81], v[166:169], v[146:149]
	v_mfma_f32_16x16x32_bf16 v[138:141], v[130:133], v[162:165], v[138:141]
	v_mfma_f32_16x16x32_bf16 v[138:141], v[142:145], v[166:169], v[138:141]
	v_mfma_f32_16x16x32_bf16 v[118:121], v[130:133], v[170:173], v[118:121]
	v_mfma_f32_16x16x32_bf16 v[118:121], v[142:145], v[174:177], v[118:121]
	v_mfma_f32_16x16x32_bf16 v[102:105], v[130:133], v[184:187], v[102:105]
	v_mfma_f32_16x16x32_bf16 v[102:105], v[142:145], v[194:197], v[102:105]
	v_mfma_f32_16x16x32_bf16 v[86:89], v[130:133], v[198:201], v[86:89]
	v_mfma_f32_16x16x32_bf16 v[86:89], v[142:145], v[202:205], v[86:89]
	v_mfma_f32_16x16x32_bf16 v[82:85], v[154:157], v[198:201], v[82:85]
	v_mfma_f32_16x16x32_bf16 v[82:85], v[158:161], v[202:205], v[82:85]
	v_mfma_f32_16x16x32_bf16 v[98:101], v[154:157], v[184:187], v[98:101]
	v_mfma_f32_16x16x32_bf16 v[98:101], v[158:161], v[194:197], v[98:101]
	v_mfma_f32_16x16x32_bf16 v[114:117], v[154:157], v[170:173], v[114:117]
	v_mfma_f32_16x16x32_bf16 v[114:117], v[158:161], v[174:177], v[114:117]
	v_mfma_f32_16x16x32_bf16 v[134:137], v[154:157], v[162:165], v[134:137]
	v_mfma_f32_16x16x32_bf16 v[134:137], v[158:161], v[166:169], v[134:137]
	s_barrier
; #define PG8_STAGE(bufoff, gbase, voff) do { _Pragma("unroll") for (int _i = 0; _i < 2; ++_i) \
;         __builtin_amdgcn_global_load_lds((const unsigned*)((const char*)(gbase) + (voff)[_i]), (PG8_LAS unsigned*)(lds + (bufoff) + ldsw + _i * 8192), 16, 0, 0); } while (0)
; #define PG8_LDA(dst, b, h) do { _Pragma("unroll") for (int m = 0; m < 4; ++m) _Pragma("unroll") for (int k = 0; k < 2; ++k) dst[m][k] = *(const PG8_LAS bf16x8*)(lds + PG8_SA(b, h) + aoff + m * 2048 + k * 1024); } while (0)
; #define PG8_WAIT_V(n) asm volatile("s_waitcnt vmcnt(" #n ")" ::: "memory")
; #define PG8_WAIT_L(n) asm volatile("s_waitcnt lgkmcnt(" #n ")" ::: "memory")
; #define PG8_BAR __builtin_amdgcn_s_barrier()
; #define PG8_SCHED __builtin_amdgcn_sched_barrier(0)
;     ...
;             PG8_WAIT_V(8); PG8_WAIT_L(0); PG8_BAR; PG8_MMA(0, 0, At, B0); PG8_MMA(0, 1, At, B1); PG8_BAR; PG8_SCHED;
;             PG8_LDA(At, 1, 1); PG8_STAGE(PG8_SB(1, 0), b3, voffB); PG8_STAGE(PG8_SB(1, 1), b3 + hstep, voffB); PG8_STAGE(PG8_SA(1, 0), a3, voffA);
;             PG8_WAIT_V(8); PG8_WAIT_L(0); PG8_BAR; PG8_MMA(1, 0, At, B0); PG8_MMA(1, 1, At, B1); PG8_BAR; PG8_SCHED;
	s_setprio 0
	s_add_i32 s8, s46, s90
	s_mov_b32 m0, s8
	ds_read_b128 v[162:165], v246 offset:49152
	ds_read_b128 v[166:169], v246 offset:50176
	ds_read_b128 v[170:173], v246 offset:51200
	ds_read_b128 v[174:177], v246 offset:52224
	ds_read_b128 v[184:187], v246 offset:53248
	ds_read_b128 v[194:197], v246 offset:54272
	ds_read_b128 v[198:201], v246 offset:55296
	ds_read_b128 v[202:205], v246 offset:56320
	s_add_u32 s100, s80, 0x80
	s_addc_u32 s101, s81, 0
	global_load_lds_dwordx4 v182, s[100:101]
	s_add_i32 m0, s8, 0x2000
	s_add_u32 s8, s80, 0x158080
	s_addc_u32 s9, s81, 0
	s_add_i32 vcc_lo, s47, s90
	global_load_lds_dwordx4 v188, s[100:101]
	s_mov_b32 m0, vcc_lo
	s_nop 0
	global_load_lds_dwordx4 v182, s[8:9]
	s_add_i32 m0, vcc_lo, 0x2000
	s_nop 0
	global_load_lds_dwordx4 v188, s[8:9]
	s_mov_b32 m0, s31
	s_nop 0
	s_add_u32 s100, s40, 0x80
	s_addc_u32 s101, s41, 0
	global_load_lds_dwordx4 v178, s[100:101]
	s_mov_b32 m0, s56
	s_nop 0
	global_load_lds_dwordx4 v180, s[100:101]
	s_waitcnt vmcnt(8)
	s_waitcnt lgkmcnt(0)
	s_setprio 1
	s_barrier
	v_mfma_f32_16x16x32_bf16 v[70:73], v[58:61], v[162:165], v[70:73]
	v_mfma_f32_16x16x32_bf16 v[70:73], v[62:65], v[166:169], v[70:73]
	v_mfma_f32_16x16x32_bf16 v[46:49], v[58:61], v[170:173], v[46:49]
	v_mfma_f32_16x16x32_bf16 v[46:49], v[62:65], v[174:177], v[46:49]
	v_mfma_f32_16x16x32_bf16 v[30:33], v[58:61], v[184:187], v[30:33]
	v_mfma_f32_16x16x32_bf16 v[30:33], v[62:65], v[194:197], v[30:33]
	v_mfma_f32_16x16x32_bf16 v[14:17], v[58:61], v[198:201], v[14:17]
	v_mfma_f32_16x16x32_bf16 v[14:17], v[62:65], v[202:205], v[14:17]
	v_mfma_f32_16x16x32_bf16 v[10:13], v[74:77], v[198:201], v[10:13]
	v_mfma_f32_16x16x32_bf16 v[10:13], v[78:81], v[202:205], v[10:13]
	v_mfma_f32_16x16x32_bf16 v[26:29], v[74:77], v[184:187], v[26:29]
	v_mfma_f32_16x16x32_bf16 v[26:29], v[78:81], v[194:197], v[26:29]
	v_mfma_f32_16x16x32_bf16 v[42:45], v[74:77], v[170:173], v[42:45]
	v_mfma_f32_16x16x32_bf16 v[42:45], v[78:81], v[174:177], v[42:45]
	v_mfma_f32_16x16x32_bf16 v[66:69], v[74:77], v[162:165], v[66:69]
	v_mfma_f32_16x16x32_bf16 v[66:69], v[78:81], v[166:169], v[66:69]
	v_mfma_f32_16x16x32_bf16 v[54:57], v[130:133], v[162:165], v[54:57]
	v_mfma_f32_16x16x32_bf16 v[54:57], v[142:145], v[166:169], v[54:57]
	v_mfma_f32_16x16x32_bf16 v[38:41], v[130:133], v[170:173], v[38:41]
	v_mfma_f32_16x16x32_bf16 v[38:41], v[142:145], v[174:177], v[38:41]
	v_mfma_f32_16x16x32_bf16 v[22:25], v[130:133], v[184:187], v[22:25]
	v_mfma_f32_16x16x32_bf16 v[22:25], v[142:145], v[194:197], v[22:25]
	v_mfma_f32_16x16x32_bf16 v[6:9], v[130:133], v[198:201], v[6:9]
	v_mfma_f32_16x16x32_bf16 v[6:9], v[142:145], v[202:205], v[6:9]
	v_mfma_f32_16x16x32_bf16 v[2:5], v[154:157], v[198:201], v[2:5]
	v_mfma_f32_16x16x32_bf16 v[2:5], v[158:161], v[202:205], v[2:5]
	v_mfma_f32_16x16x32_bf16 v[18:21], v[154:157], v[184:187], v[18:21]
	v_mfma_f32_16x16x32_bf16 v[18:21], v[158:161], v[194:197], v[18:21]
	v_mfma_f32_16x16x32_bf16 v[34:37], v[154:157], v[170:173], v[34:37]
	v_mfma_f32_16x16x32_bf16 v[34:37], v[158:161], v[174:177], v[34:37]
	v_mfma_f32_16x16x32_bf16 v[50:53], v[154:157], v[162:165], v[50:53]
	v_mfma_f32_16x16x32_bf16 v[50:53], v[158:161], v[166:169], v[50:53]
	s_barrier
	s_setprio 0
	s_add_i32 s45, s45, 2
	s_add_u32 s37, s37, 0x100
	s_addc_u32 s44, s44, 0
	s_cmpk_gt_u32 s45, 0x53
	s_mov_b64 s[8:9], s[10:11]
	s_mov_b32 s101, 0
	s_cbranch_scc0 .LBB0_1648
	s_branch .Lrlx_f2_x

; #define PG8_BAR __builtin_amdgcn_s_barrier()
;     ...
;         }
;         unsigned long long tp0 = 0; if constexpr (TP == 1) tp0 = __builtin_amdgcn_s_memrealtime();
;         if constexpr (ALIGN_EPI) { if (wr == 0) PG8_BAR; }
.Lrlx_f2_x:
	s_and_b64 vcc, exec, s[76:77]
	s_cbranch_vccz .LBB0_1651
	s_barrier
